# snake of accumulate chains extended over the whole 32-MFMA segment (15 of 16 chain boundaries share a source operand)
# baseline (speedup 1.0000x reference)
; #define PG8_STAGE(bufoff, gbase, voff) do { _Pragma("unroll") for (int _i = 0; _i < 2; ++_i) \
;         __builtin_amdgcn_global_load_lds((const unsigned*)((const char*)(gbase) + (voff)[_i]), (PG8_LAS unsigned*)(lds + (bufoff) + ldsw + _i * 8192), 16, 0, 0); } while (0)
; #define PG8_LDA(dst, b, h) do { _Pragma("unroll") for (int m = 0; m < 4; ++m) _Pragma("unroll") for (int k = 0; k < 2; ++k) dst[m][k] = *(const PG8_LAS bf16x8*)(lds + PG8_SA(b, h) + aoff + m * 2048 + k * 1024); } while (0)
; #define PG8_LDB(dst, b, h) do { _Pragma("unroll") for (int n = 0; n < 2; ++n) _Pragma("unroll") for (int k = 0; k < 2; ++k) dst[n][k] = *(const PG8_LAS bf16x8*)(lds + PG8_SB(b, h) + boff + n * 2048 + k * 1024); } while (0)
; #define PG8_MMA(ai, bj, At, Bt) do { __builtin_amdgcn_s_setprio(1); _Pragma("unroll") for (int m = 0; m < 4; ++m) _Pragma("unroll") for (int n = 0; n < 2; ++n) _Pragma("unroll") for (int k = 0; k < 2; ++k) \
;         acc[ai][bj][m][n] = __builtin_amdgcn_mfma_f32_16x16x32_bf16(Bt[n][k], At[m][k], acc[ai][bj][m][n], 0, 0, 0); __builtin_amdgcn_s_setprio(0); } while (0)
; #define PG8_WAIT_V(n) asm volatile("s_waitcnt vmcnt(" #n ")" ::: "memory")
; #define PG8_BAR __builtin_amdgcn_s_barrier()
; template <class Epi, class Sched, bool ALIGN_EPI = false, bool SP2 = false, bool ABLK = false, bool BBLK = false>
; __device__ __forceinline__ void gemm_phase(PG8_LAS unsigned char* lds, const Gemm g, const Sched& S, const Epi& E) {
;     ...
;             const bool last = (t == nt - 2);
;             const char* a1 = cA + (size_t)(t + 1) * kstepA;
;             const char* a2 = last ? nA : cA + (size_t)(t + 2) * kstepA; const char* b2 = last ? nB : cB + (size_t)(t + 2) * kstepB;
;             const char* a3 = a2 + kstepA; const char* b3 = b2 + kstepB;
;             if (last && has_next) S.a_ready(nxt);
;             if constexpr (SP2) {
;             PG8_LDB(B0, 0, 0); PG8_LDB(B1, 0, 1); PG8_SCHED; PG8_LDA(At, 0, 0); PG8_STAGE(PG8_SA(1, 1), a1 + hstepA, voffA);
;             PG8_WAIT_V(8); PG8_WAIT_L(0); PG8_BAR; PG8_MMA(0, 0, At, B0); PG8_MMA(0, 1, At, B1); PG8_BAR; PG8_SCHED;
;             PG8_LDA(At, 0, 1); PG8_STAGE(PG8_SB(0, 0), b2, voffB); PG8_STAGE(PG8_SB(0, 1), b2 + hstepB, voffB); PG8_STAGE(PG8_SA(0, 0), a2, voffA);
;             PG8_WAIT_V(8); PG8_WAIT_L(0); PG8_BAR; PG8_MMA(1, 0, At, B0); PG8_MMA(1, 1, At, B1); PG8_BAR; PG8_SCHED;
.LBB0_185:
	s_add_u32 s13, s20, 0x4000
	s_addc_u32 s22, s21, 0
	s_cmp_eq_u32 vcc_hi, 28
	s_cselect_b32 s26, s70, s13
	s_cselect_b32 s27, s9, s22
	s_cselect_b32 s24, s71, s77
	s_cselect_b32 s25, s7, vcc_lo
	s_add_u32 s22, s26, 0x8000
	s_addc_u32 s23, s27, 0
	s_add_i32 s13, 0, 0x10000
	v_add_u32_e32 v36, s13, v160
	s_add_i32 s88, 0, 0x14000
	ds_read_b128 v[152:155], v36
	ds_read_b128 v[156:159], v36 offset:1024
	ds_read_b128 v[162:165], v36 offset:2048
	ds_read_b128 v[166:169], v36 offset:3072
	v_add_u32_e32 v36, s88, v160
	ds_read_b128 v[170:173], v36
	ds_read_b128 v[174:177], v36 offset:1024
	ds_read_b128 v[178:181], v36 offset:2048
	ds_read_b128 v[182:185], v36 offset:3072
	s_add_i32 m0, s19, 0xc000
	ds_read_b128 v[186:189], v161
	ds_read_b128 v[190:193], v161 offset:1024
	ds_read_b128 v[194:197], v161 offset:2048
	ds_read_b128 v[198:201], v161 offset:3072
	ds_read_b128 v[202:205], v161 offset:4096
	ds_read_b128 v[206:209], v161 offset:5120
	ds_read_b128 v[210:213], v161 offset:6144
	ds_read_b128 v[214:217], v161 offset:7168
	global_load_lds_dwordx4 v148, s[20:21]
	s_add_i32 m0, s19, 0xe000
	s_nop 0
	global_load_lds_dwordx4 v150, s[20:21]
	s_waitcnt vmcnt(8)
	s_waitcnt lgkmcnt(0)
	v_mfma_f32_16x16x32_bf16 v[132:135], v[152:155], v[186:189], v[132:135]
	v_mfma_f32_16x16x32_bf16 v[132:135], v[156:159], v[190:193], v[132:135]
	v_mfma_f32_16x16x32_bf16 v[128:131], v[166:169], v[190:193], v[128:131]
	v_mfma_f32_16x16x32_bf16 v[128:131], v[162:165], v[186:189], v[128:131]
	s_barrier
	s_setprio 1
	v_mfma_f32_16x16x32_bf16 v[112:115], v[162:165], v[194:197], v[112:115]
	v_mfma_f32_16x16x32_bf16 v[112:115], v[166:169], v[198:201], v[112:115]
	v_mfma_f32_16x16x32_bf16 v[116:119], v[156:159], v[198:201], v[116:119]
	v_mfma_f32_16x16x32_bf16 v[116:119], v[152:155], v[194:197], v[116:119]
	v_mfma_f32_16x16x32_bf16 v[100:103], v[152:155], v[202:205], v[100:103]
	v_mfma_f32_16x16x32_bf16 v[100:103], v[156:159], v[206:209], v[100:103]
	v_mfma_f32_16x16x32_bf16 v[96:99], v[166:169], v[206:209], v[96:99]
	v_mfma_f32_16x16x32_bf16 v[96:99], v[162:165], v[202:205], v[96:99]
	v_mfma_f32_16x16x32_bf16 v[80:83], v[162:165], v[210:213], v[80:83]
	v_mfma_f32_16x16x32_bf16 v[80:83], v[166:169], v[214:217], v[80:83]
	v_mfma_f32_16x16x32_bf16 v[84:87], v[156:159], v[214:217], v[84:87]
	v_mfma_f32_16x16x32_bf16 v[84:87], v[152:155], v[210:213], v[84:87]
	s_setprio 0
	s_setprio 1
	v_mfma_f32_16x16x32_bf16 v[76:79], v[170:173], v[210:213], v[76:79]
	v_mfma_f32_16x16x32_bf16 v[76:79], v[174:177], v[214:217], v[76:79]
	v_mfma_f32_16x16x32_bf16 v[124:127], v[174:177], v[190:193], v[124:127]
	v_mfma_f32_16x16x32_bf16 v[124:127], v[170:173], v[186:189], v[124:127]
	v_mfma_f32_16x16x32_bf16 v[120:123], v[178:181], v[186:189], v[120:123]
	v_mfma_f32_16x16x32_bf16 v[120:123], v[182:185], v[190:193], v[120:123]
	v_mfma_f32_16x16x32_bf16 v[104:107], v[182:185], v[198:201], v[104:107]
	v_mfma_f32_16x16x32_bf16 v[104:107], v[178:181], v[194:197], v[104:107]
	v_mfma_f32_16x16x32_bf16 v[108:111], v[170:173], v[194:197], v[108:111]
	v_mfma_f32_16x16x32_bf16 v[108:111], v[174:177], v[198:201], v[108:111]
	v_mfma_f32_16x16x32_bf16 v[92:95], v[174:177], v[206:209], v[92:95]
	v_mfma_f32_16x16x32_bf16 v[92:95], v[170:173], v[202:205], v[92:95]
	v_mfma_f32_16x16x32_bf16 v[88:91], v[178:181], v[202:205], v[88:91]
	v_mfma_f32_16x16x32_bf16 v[88:91], v[182:185], v[206:209], v[88:91]
	v_mfma_f32_16x16x32_bf16 v[72:75], v[182:185], v[214:217], v[72:75]
	v_mfma_f32_16x16x32_bf16 v[72:75], v[178:181], v[210:213], v[72:75]
	s_setprio 0
	s_barrier
	s_add_i32 s13, s13, s31
	s_mov_b32 m0, s13
	ds_read_b128 v[186:189], v161 offset:16384
	ds_read_b128 v[190:193], v161 offset:17408
	ds_read_b128 v[194:197], v161 offset:18432
	ds_read_b128 v[198:201], v161 offset:19456
	ds_read_b128 v[202:205], v161 offset:20480
	ds_read_b128 v[206:209], v161 offset:21504
	ds_read_b128 v[210:213], v161 offset:22528
	ds_read_b128 v[214:217], v161 offset:23552
	global_load_lds_dwordx4 v140, s[24:25]
	s_add_i32 m0, s13, 0x2000
	s_add_u32 s68, s24, 0x4000
	s_addc_u32 s69, s25, 0
	s_add_i32 s13, s88, s31
	global_load_lds_dwordx4 v136, s[24:25]
	s_mov_b32 m0, s13
	s_nop 0
	global_load_lds_dwordx4 v140, s[68:69]
	s_add_i32 m0, s13, 0x2000
	s_nop 0
	global_load_lds_dwordx4 v136, s[68:69]
	s_mov_b32 m0, s19
	s_nop 0
	global_load_lds_dwordx4 v142, s[26:27]
	s_mov_b32 m0, s35
	s_nop 0
	global_load_lds_dwordx4 v138, s[26:27]
	s_waitcnt vmcnt(8)
	s_waitcnt lgkmcnt(0)
	v_mfma_f32_16x16x32_bf16 v[68:71], v[152:155], v[186:189], v[68:71]
	v_mfma_f32_16x16x32_bf16 v[68:71], v[156:159], v[190:193], v[68:71]
	v_mfma_f32_16x16x32_bf16 v[64:67], v[166:169], v[190:193], v[64:67]
	v_mfma_f32_16x16x32_bf16 v[64:67], v[162:165], v[186:189], v[64:67]
	s_barrier
; #define PG8_STAGE(bufoff, gbase, voff) do { _Pragma("unroll") for (int _i = 0; _i < 2; ++_i) \
;         __builtin_amdgcn_global_load_lds((const unsigned*)((const char*)(gbase) + (voff)[_i]), (PG8_LAS unsigned*)(lds + (bufoff) + ldsw + _i * 8192), 16, 0, 0); } while (0)
; #define PG8_LDA(dst, b, h) do { _Pragma("unroll") for (int m = 0; m < 4; ++m) _Pragma("unroll") for (int k = 0; k < 2; ++k) dst[m][k] = *(const PG8_LAS bf16x8*)(lds + PG8_SA(b, h) + aoff + m * 2048 + k * 1024); } while (0)
; #define PG8_LDB(dst, b, h) do { _Pragma("unroll") for (int n = 0; n < 2; ++n) _Pragma("unroll") for (int k = 0; k < 2; ++k) dst[n][k] = *(const PG8_LAS bf16x8*)(lds + PG8_SB(b, h) + boff + n * 2048 + k * 1024); } while (0)
; #define PG8_MMA(ai, bj, At, Bt) do { __builtin_amdgcn_s_setprio(1); _Pragma("unroll") for (int m = 0; m < 4; ++m) _Pragma("unroll") for (int n = 0; n < 2; ++n) _Pragma("unroll") for (int k = 0; k < 2; ++k) \
;         acc[ai][bj][m][n] = __builtin_amdgcn_mfma_f32_16x16x32_bf16(Bt[n][k], At[m][k], acc[ai][bj][m][n], 0, 0, 0); __builtin_amdgcn_s_setprio(0); } while (0)
; #define PG8_WAIT_V(n) asm volatile("s_waitcnt vmcnt(" #n ")" ::: "memory")
; #define PG8_WAIT_L(n) asm volatile("s_waitcnt lgkmcnt(" #n ")" ::: "memory")
; #define PG8_BAR __builtin_amdgcn_s_barrier()
; #define PG8_SCHED __builtin_amdgcn_sched_barrier(0)
; template <class Epi, class Sched, bool ALIGN_EPI = false, bool SP2 = false, bool ABLK = false, bool BBLK = false>
; __device__ __forceinline__ void gemm_phase(PG8_LAS unsigned char* lds, const Gemm g, const Sched& S, const Epi& E) {
;     ...
;             PG8_WAIT_V(8); PG8_WAIT_L(0); PG8_BAR; PG8_MMA(1, 0, At, B0); PG8_MMA(1, 1, At, B1); PG8_BAR; PG8_SCHED;
;             PG8_LDB(B0, 1, 0); PG8_LDB(B1, 1, 1); PG8_SCHED; PG8_LDA(At, 1, 0); PG8_STAGE(PG8_SA(0, 1), a2 + hstepA, voffA);
;             PG8_WAIT_V(8); PG8_WAIT_L(0); PG8_BAR; PG8_MMA(0, 0, At, B0); PG8_MMA(0, 1, At, B1); PG8_BAR; PG8_SCHED;
	s_setprio 1
	v_mfma_f32_16x16x32_bf16 v[48:51], v[162:165], v[194:197], v[48:51]
	v_mfma_f32_16x16x32_bf16 v[48:51], v[166:169], v[198:201], v[48:51]
	v_mfma_f32_16x16x32_bf16 v[52:55], v[156:159], v[198:201], v[52:55]
	v_mfma_f32_16x16x32_bf16 v[52:55], v[152:155], v[194:197], v[52:55]
	v_mfma_f32_16x16x32_bf16 v[32:35], v[152:155], v[202:205], v[32:35]
	v_mfma_f32_16x16x32_bf16 v[32:35], v[156:159], v[206:209], v[32:35]
	v_mfma_f32_16x16x32_bf16 v[28:31], v[166:169], v[206:209], v[28:31]
	v_mfma_f32_16x16x32_bf16 v[28:31], v[162:165], v[202:205], v[28:31]
	v_mfma_f32_16x16x32_bf16 v[12:15], v[162:165], v[210:213], v[12:15]
	v_mfma_f32_16x16x32_bf16 v[12:15], v[166:169], v[214:217], v[12:15]
	v_mfma_f32_16x16x32_bf16 v[16:19], v[156:159], v[214:217], v[16:19]
	v_mfma_f32_16x16x32_bf16 v[16:19], v[152:155], v[210:213], v[16:19]
	s_setprio 0
	s_setprio 1
	v_mfma_f32_16x16x32_bf16 v[8:11], v[170:173], v[210:213], v[8:11]
	v_mfma_f32_16x16x32_bf16 v[8:11], v[174:177], v[214:217], v[8:11]
	v_mfma_f32_16x16x32_bf16 v[60:63], v[174:177], v[190:193], v[60:63]
	v_mfma_f32_16x16x32_bf16 v[60:63], v[170:173], v[186:189], v[60:63]
	v_mfma_f32_16x16x32_bf16 v[56:59], v[178:181], v[186:189], v[56:59]
	v_mfma_f32_16x16x32_bf16 v[56:59], v[182:185], v[190:193], v[56:59]
	v_mfma_f32_16x16x32_bf16 v[40:43], v[182:185], v[198:201], v[40:43]
	v_mfma_f32_16x16x32_bf16 v[40:43], v[178:181], v[194:197], v[40:43]
	v_mfma_f32_16x16x32_bf16 v[44:47], v[170:173], v[194:197], v[44:47]
	v_mfma_f32_16x16x32_bf16 v[44:47], v[174:177], v[198:201], v[44:47]
	v_mfma_f32_16x16x32_bf16 v[24:27], v[174:177], v[206:209], v[24:27]
	v_mfma_f32_16x16x32_bf16 v[24:27], v[170:173], v[202:205], v[24:27]
	v_mfma_f32_16x16x32_bf16 v[20:23], v[178:181], v[202:205], v[20:23]
	v_mfma_f32_16x16x32_bf16 v[20:23], v[182:185], v[206:209], v[20:23]
	v_mfma_f32_16x16x32_bf16 v[4:7], v[182:185], v[214:217], v[4:7]
	v_mfma_f32_16x16x32_bf16 v[4:7], v[178:181], v[210:213], v[4:7]
	s_setprio 0
	s_barrier
	s_add_i32 s13, 0, 0x18000
	v_add_u32_e32 v36, s13, v160
	s_add_i32 s68, 0, 0x1c000
	ds_read_b128 v[152:155], v36
	ds_read_b128 v[156:159], v36 offset:1024
	ds_read_b128 v[162:165], v36 offset:2048
	ds_read_b128 v[166:169], v36 offset:3072
	v_add_u32_e32 v36, s68, v160
	ds_read_b128 v[170:173], v36
	ds_read_b128 v[174:177], v36 offset:1024
	ds_read_b128 v[178:181], v36 offset:2048
	ds_read_b128 v[182:185], v36 offset:3072
	s_add_u32 s26, s26, 0x4000
	s_addc_u32 s27, s27, 0
	s_mov_b32 m0, s36
	ds_read_b128 v[186:189], v161 offset:32768
	ds_read_b128 v[190:193], v161 offset:33792
	ds_read_b128 v[194:197], v161 offset:34816
	ds_read_b128 v[198:201], v161 offset:35840
	ds_read_b128 v[202:205], v161 offset:36864
	ds_read_b128 v[206:209], v161 offset:37888
	ds_read_b128 v[210:213], v161 offset:38912
	ds_read_b128 v[214:217], v161 offset:39936
	global_load_lds_dwordx4 v142, s[26:27]
	s_mov_b32 m0, s37
	s_nop 0
	global_load_lds_dwordx4 v138, s[26:27]
	s_waitcnt vmcnt(8)
	s_waitcnt lgkmcnt(0)
	v_mfma_f32_16x16x32_bf16 v[132:135], v[152:155], v[186:189], v[132:135]
	v_mfma_f32_16x16x32_bf16 v[132:135], v[156:159], v[190:193], v[132:135]
	v_mfma_f32_16x16x32_bf16 v[128:131], v[166:169], v[190:193], v[128:131]
	v_mfma_f32_16x16x32_bf16 v[128:131], v[162:165], v[186:189], v[128:131]
	s_barrier
	s_setprio 1
	v_mfma_f32_16x16x32_bf16 v[112:115], v[162:165], v[194:197], v[112:115]
	v_mfma_f32_16x16x32_bf16 v[112:115], v[166:169], v[198:201], v[112:115]
	v_mfma_f32_16x16x32_bf16 v[116:119], v[156:159], v[198:201], v[116:119]
	v_mfma_f32_16x16x32_bf16 v[116:119], v[152:155], v[194:197], v[116:119]
	v_mfma_f32_16x16x32_bf16 v[100:103], v[152:155], v[202:205], v[100:103]
	v_mfma_f32_16x16x32_bf16 v[100:103], v[156:159], v[206:209], v[100:103]
	v_mfma_f32_16x16x32_bf16 v[96:99], v[166:169], v[206:209], v[96:99]
	v_mfma_f32_16x16x32_bf16 v[96:99], v[162:165], v[202:205], v[96:99]
	v_mfma_f32_16x16x32_bf16 v[80:83], v[162:165], v[210:213], v[80:83]
	v_mfma_f32_16x16x32_bf16 v[80:83], v[166:169], v[214:217], v[80:83]
	v_mfma_f32_16x16x32_bf16 v[84:87], v[156:159], v[214:217], v[84:87]
	v_mfma_f32_16x16x32_bf16 v[84:87], v[152:155], v[210:213], v[84:87]
	s_setprio 0
	s_setprio 1
	v_mfma_f32_16x16x32_bf16 v[76:79], v[170:173], v[210:213], v[76:79]
	v_mfma_f32_16x16x32_bf16 v[76:79], v[174:177], v[214:217], v[76:79]
	v_mfma_f32_16x16x32_bf16 v[124:127], v[174:177], v[190:193], v[124:127]
	v_mfma_f32_16x16x32_bf16 v[124:127], v[170:173], v[186:189], v[124:127]
	v_mfma_f32_16x16x32_bf16 v[120:123], v[178:181], v[186:189], v[120:123]
	v_mfma_f32_16x16x32_bf16 v[120:123], v[182:185], v[190:193], v[120:123]
	v_mfma_f32_16x16x32_bf16 v[104:107], v[182:185], v[198:201], v[104:107]
	v_mfma_f32_16x16x32_bf16 v[104:107], v[178:181], v[194:197], v[104:107]
	v_mfma_f32_16x16x32_bf16 v[108:111], v[170:173], v[194:197], v[108:111]
	v_mfma_f32_16x16x32_bf16 v[108:111], v[174:177], v[198:201], v[108:111]
	v_mfma_f32_16x16x32_bf16 v[92:95], v[174:177], v[206:209], v[92:95]
	v_mfma_f32_16x16x32_bf16 v[92:95], v[170:173], v[202:205], v[92:95]
	v_mfma_f32_16x16x32_bf16 v[88:91], v[178:181], v[202:205], v[88:91]
	v_mfma_f32_16x16x32_bf16 v[88:91], v[182:185], v[206:209], v[88:91]
	v_mfma_f32_16x16x32_bf16 v[72:75], v[182:185], v[214:217], v[72:75]
	v_mfma_f32_16x16x32_bf16 v[72:75], v[178:181], v[210:213], v[72:75]
	s_setprio 0
	s_barrier
; #define PG8_STAGE(bufoff, gbase, voff) do { _Pragma("unroll") for (int _i = 0; _i < 2; ++_i) \
;         __builtin_amdgcn_global_load_lds((const unsigned*)((const char*)(gbase) + (voff)[_i]), (PG8_LAS unsigned*)(lds + (bufoff) + ldsw + _i * 8192), 16, 0, 0); } while (0)
; #define PG8_LDA(dst, b, h) do { _Pragma("unroll") for (int m = 0; m < 4; ++m) _Pragma("unroll") for (int k = 0; k < 2; ++k) dst[m][k] = *(const PG8_LAS bf16x8*)(lds + PG8_SA(b, h) + aoff + m * 2048 + k * 1024); } while (0)
; #define PG8_MMA(ai, bj, At, Bt) do { __builtin_amdgcn_s_setprio(1); _Pragma("unroll") for (int m = 0; m < 4; ++m) _Pragma("unroll") for (int n = 0; n < 2; ++n) _Pragma("unroll") for (int k = 0; k < 2; ++k) \
;         acc[ai][bj][m][n] = __builtin_amdgcn_mfma_f32_16x16x32_bf16(Bt[n][k], At[m][k], acc[ai][bj][m][n], 0, 0, 0); __builtin_amdgcn_s_setprio(0); } while (0)
; #define PG8_WAIT_V(n) asm volatile("s_waitcnt vmcnt(" #n ")" ::: "memory")
; #define PG8_WAIT_L(n) asm volatile("s_waitcnt lgkmcnt(" #n ")" ::: "memory")
; #define PG8_BAR __builtin_amdgcn_s_barrier()
; #define PG8_SCHED __builtin_amdgcn_sched_barrier(0)
; template <class Epi, class Sched, bool ALIGN_EPI = false, bool SP2 = false, bool ABLK = false, bool BBLK = false>
; __device__ __forceinline__ void gemm_phase(PG8_LAS unsigned char* lds, const Gemm g, const Sched& S, const Epi& E) {
;     ...
;             PG8_LDA(At, 1, 1); PG8_STAGE(PG8_SB(1, 0), b3, voffB); PG8_STAGE(PG8_SB(1, 1), b3 + hstepB, voffB); PG8_STAGE(PG8_SA(1, 0), a3, voffA);
;             PG8_WAIT_V(8); PG8_WAIT_L(0); PG8_BAR; PG8_MMA(1, 0, At, B0); PG8_MMA(1, 1, At, B1); PG8_BAR; PG8_SCHED;
;     ...
;         if constexpr (ALIGN_EPI) { if (wr == 0) PG8_BAR; }
	s_add_u32 s26, s24, 0x8000
	s_addc_u32 s27, s25, 0
	s_add_i32 s13, s13, s31
	s_mov_b32 m0, s13
	ds_read_b128 v[186:189], v161 offset:49152
	ds_read_b128 v[190:193], v161 offset:50176
	ds_read_b128 v[194:197], v161 offset:51200
	ds_read_b128 v[198:201], v161 offset:52224
	ds_read_b128 v[202:205], v161 offset:53248
	ds_read_b128 v[206:209], v161 offset:54272
	ds_read_b128 v[210:213], v161 offset:55296
	ds_read_b128 v[214:217], v161 offset:56320
	global_load_lds_dwordx4 v140, s[26:27]
	s_add_i32 m0, s13, 0x2000
	s_add_u32 s24, s24, 0xc000
	s_addc_u32 s25, s25, 0
	s_add_i32 s13, s68, s31
	global_load_lds_dwordx4 v136, s[26:27]
	s_mov_b32 m0, s13
	s_nop 0
	global_load_lds_dwordx4 v140, s[24:25]
	s_add_i32 m0, s13, 0x2000
	s_nop 0
	global_load_lds_dwordx4 v136, s[24:25]
	s_mov_b32 m0, s62
	s_nop 0
	global_load_lds_dwordx4 v142, s[22:23]
	s_mov_b32 m0, s63
	s_nop 0
	global_load_lds_dwordx4 v138, s[22:23]
	s_waitcnt vmcnt(8)
	s_waitcnt lgkmcnt(0)
	v_mfma_f32_16x16x32_bf16 v[68:71], v[152:155], v[186:189], v[68:71]
	v_mfma_f32_16x16x32_bf16 v[68:71], v[156:159], v[190:193], v[68:71]
	v_mfma_f32_16x16x32_bf16 v[64:67], v[166:169], v[190:193], v[64:67]
	v_mfma_f32_16x16x32_bf16 v[64:67], v[162:165], v[186:189], v[64:67]
	s_barrier
	s_setprio 1
	v_mfma_f32_16x16x32_bf16 v[48:51], v[162:165], v[194:197], v[48:51]
	v_mfma_f32_16x16x32_bf16 v[48:51], v[166:169], v[198:201], v[48:51]
	v_mfma_f32_16x16x32_bf16 v[52:55], v[156:159], v[198:201], v[52:55]
	v_mfma_f32_16x16x32_bf16 v[52:55], v[152:155], v[194:197], v[52:55]
	v_mfma_f32_16x16x32_bf16 v[32:35], v[152:155], v[202:205], v[32:35]
	v_mfma_f32_16x16x32_bf16 v[32:35], v[156:159], v[206:209], v[32:35]
	v_mfma_f32_16x16x32_bf16 v[28:31], v[166:169], v[206:209], v[28:31]
	v_mfma_f32_16x16x32_bf16 v[28:31], v[162:165], v[202:205], v[28:31]
	v_mfma_f32_16x16x32_bf16 v[12:15], v[162:165], v[210:213], v[12:15]
	v_mfma_f32_16x16x32_bf16 v[12:15], v[166:169], v[214:217], v[12:15]
	v_mfma_f32_16x16x32_bf16 v[16:19], v[156:159], v[214:217], v[16:19]
	v_mfma_f32_16x16x32_bf16 v[16:19], v[152:155], v[210:213], v[16:19]
	s_setprio 0
	s_setprio 1
	v_mfma_f32_16x16x32_bf16 v[8:11], v[170:173], v[210:213], v[8:11]
	v_mfma_f32_16x16x32_bf16 v[8:11], v[174:177], v[214:217], v[8:11]
	v_mfma_f32_16x16x32_bf16 v[60:63], v[174:177], v[190:193], v[60:63]
	v_mfma_f32_16x16x32_bf16 v[60:63], v[170:173], v[186:189], v[60:63]
	v_mfma_f32_16x16x32_bf16 v[56:59], v[178:181], v[186:189], v[56:59]
	v_mfma_f32_16x16x32_bf16 v[56:59], v[182:185], v[190:193], v[56:59]
	v_mfma_f32_16x16x32_bf16 v[40:43], v[182:185], v[198:201], v[40:43]
	v_mfma_f32_16x16x32_bf16 v[40:43], v[178:181], v[194:197], v[40:43]
	v_mfma_f32_16x16x32_bf16 v[44:47], v[170:173], v[194:197], v[44:47]
	v_mfma_f32_16x16x32_bf16 v[44:47], v[174:177], v[198:201], v[44:47]
	v_mfma_f32_16x16x32_bf16 v[24:27], v[174:177], v[206:209], v[24:27]
	v_mfma_f32_16x16x32_bf16 v[24:27], v[170:173], v[202:205], v[24:27]
	v_mfma_f32_16x16x32_bf16 v[20:23], v[178:181], v[202:205], v[20:23]
	v_mfma_f32_16x16x32_bf16 v[20:23], v[182:185], v[206:209], v[20:23]
	v_mfma_f32_16x16x32_bf16 v[4:7], v[182:185], v[214:217], v[4:7]
	v_mfma_f32_16x16x32_bf16 v[4:7], v[178:181], v[210:213], v[4:7]
	s_setprio 0
	s_barrier
	s_add_i32 vcc_hi, vcc_hi, 2
	s_add_u32 s20, s20, 0x10000
	s_addc_u32 s21, s21, 0
	s_add_u32 s77, s77, 0x10000
	s_addc_u32 vcc_lo, vcc_lo, 0
	s_cmp_gt_u32 vcc_hi, 29
	s_cbranch_scc0 .LBB0_185
	s_and_b64 vcc, exec, s[4:5]
	s_cbranch_vccz .LBB0_188
	s_barrier

; #define PG8_STAGE(bufoff, gbase, voff) do { _Pragma("unroll") for (int _i = 0; _i < 2; ++_i) \
;         __builtin_amdgcn_global_load_lds((const unsigned*)((const char*)(gbase) + (voff)[_i]), (PG8_LAS unsigned*)(lds + (bufoff) + ldsw + _i * 8192), 16, 0, 0); } while (0)
; #define PG8_LDA(dst, b, h) do { _Pragma("unroll") for (int m = 0; m < 4; ++m) _Pragma("unroll") for (int k = 0; k < 2; ++k) dst[m][k] = *(const PG8_LAS bf16x8*)(lds + PG8_SA(b, h) + aoff + m * 2048 + k * 1024); } while (0)
; #define PG8_LDB(dst, b, h) do { _Pragma("unroll") for (int n = 0; n < 2; ++n) _Pragma("unroll") for (int k = 0; k < 2; ++k) dst[n][k] = *(const PG8_LAS bf16x8*)(lds + PG8_SB(b, h) + boff + n * 2048 + k * 1024); } while (0)
; #define PG8_MMA(ai, bj, At, Bt) do { __builtin_amdgcn_s_setprio(1); _Pragma("unroll") for (int m = 0; m < 4; ++m) _Pragma("unroll") for (int n = 0; n < 2; ++n) _Pragma("unroll") for (int k = 0; k < 2; ++k) \
;         acc[ai][bj][m][n] = __builtin_amdgcn_mfma_f32_16x16x32_bf16(Bt[n][k], At[m][k], acc[ai][bj][m][n], 0, 0, 0); __builtin_amdgcn_s_setprio(0); } while (0)
; #define PG8_WAIT_V(n) asm volatile("s_waitcnt vmcnt(" #n ")" ::: "memory")
; #define PG8_BAR __builtin_amdgcn_s_barrier()
; template <class Epi, class Sched, bool ALIGN_EPI = false, bool SP2 = false, bool ABLK = false, bool BBLK = false>
; __device__ __forceinline__ void gemm_phase(PG8_LAS unsigned char* lds, const Gemm g, const Sched& S, const Epi& E) {
;     ...
;             const bool last = (t == nt - 2);
;             const char* a1 = cA + (size_t)(t + 1) * kstepA;
;             const char* a2 = last ? nA : cA + (size_t)(t + 2) * kstepA; const char* b2 = last ? nB : cB + (size_t)(t + 2) * kstepB;
;             const char* a3 = a2 + kstepA; const char* b3 = b2 + kstepB;
;             if (last && has_next) S.a_ready(nxt);
;             if constexpr (SP2) {
;             PG8_LDB(B0, 0, 0); PG8_LDB(B1, 0, 1); PG8_SCHED; PG8_LDA(At, 0, 0); PG8_STAGE(PG8_SA(1, 1), a1 + hstepA, voffA);
;             PG8_WAIT_V(8); PG8_WAIT_L(0); PG8_BAR; PG8_MMA(0, 0, At, B0); PG8_MMA(0, 1, At, B1); PG8_BAR; PG8_SCHED;
;             PG8_LDA(At, 0, 1); PG8_STAGE(PG8_SB(0, 0), b2, voffB); PG8_STAGE(PG8_SB(0, 1), b2 + hstepB, voffB); PG8_STAGE(PG8_SA(0, 0), a2, voffA);
;             PG8_WAIT_V(8); PG8_WAIT_L(0); PG8_BAR; PG8_MMA(1, 0, At, B0); PG8_MMA(1, 1, At, B1); PG8_BAR; PG8_SCHED;
.LBB0_439:
	s_add_u32 s16, s10, 0x4000
	s_addc_u32 s17, s11, 0
	s_cmpk_eq_i32 s13, 0x54
	s_cselect_b32 s20, s0, s16
	s_cselect_b32 s21, s1, s17
	s_cselect_b32 s18, s8, vcc_lo
	s_cselect_b32 s19, s9, vcc_hi
	s_add_u32 s16, s20, 0x8000
	s_addc_u32 s17, s21, 0
	s_add_i32 s68, 0, 0x10000
	v_add_u32_e32 v36, s68, v148
	s_add_i32 s88, 0, 0x14000
	ds_read_b128 v[152:155], v36
	ds_read_b128 v[156:159], v36 offset:1024
	ds_read_b128 v[160:163], v36 offset:2048
	ds_read_b128 v[164:167], v36 offset:3072
	v_add_u32_e32 v36, s88, v148
	ds_read_b128 v[168:171], v36
	ds_read_b128 v[172:175], v36 offset:1024
	ds_read_b128 v[176:179], v36 offset:2048
	ds_read_b128 v[180:183], v36 offset:3072
	s_add_i32 m0, s27, 0xc000
	ds_read_b128 v[184:187], v150
	ds_read_b128 v[188:191], v150 offset:1024
	ds_read_b128 v[192:195], v150 offset:2048
	ds_read_b128 v[196:199], v150 offset:3072
	ds_read_b128 v[200:203], v150 offset:4096
	ds_read_b128 v[204:207], v150 offset:5120
	ds_read_b128 v[208:211], v150 offset:6144
	ds_read_b128 v[212:215], v150 offset:7168
	global_load_lds_dwordx4 v144, s[10:11]
	s_add_i32 m0, s27, 0xe000
	s_nop 0
	global_load_lds_dwordx4 v146, s[10:11]
	s_waitcnt vmcnt(8)
	s_waitcnt lgkmcnt(0)
	v_mfma_f32_16x16x32_bf16 v[132:135], v[152:155], v[184:187], v[132:135]
	v_mfma_f32_16x16x32_bf16 v[132:135], v[156:159], v[188:191], v[132:135]
	v_mfma_f32_16x16x32_bf16 v[128:131], v[164:167], v[188:191], v[128:131]
	v_mfma_f32_16x16x32_bf16 v[128:131], v[160:163], v[184:187], v[128:131]
	s_barrier
	s_setprio 1
	v_mfma_f32_16x16x32_bf16 v[120:123], v[160:163], v[192:195], v[120:123]
	v_mfma_f32_16x16x32_bf16 v[120:123], v[164:167], v[196:199], v[120:123]
	v_mfma_f32_16x16x32_bf16 v[124:127], v[156:159], v[196:199], v[124:127]
	v_mfma_f32_16x16x32_bf16 v[124:127], v[152:155], v[192:195], v[124:127]
	v_mfma_f32_16x16x32_bf16 v[108:111], v[152:155], v[200:203], v[108:111]
	v_mfma_f32_16x16x32_bf16 v[108:111], v[156:159], v[204:207], v[108:111]
	v_mfma_f32_16x16x32_bf16 v[104:107], v[164:167], v[204:207], v[104:107]
	v_mfma_f32_16x16x32_bf16 v[104:107], v[160:163], v[200:203], v[104:107]
	v_mfma_f32_16x16x32_bf16 v[88:91], v[160:163], v[208:211], v[88:91]
	v_mfma_f32_16x16x32_bf16 v[88:91], v[164:167], v[212:215], v[88:91]
	v_mfma_f32_16x16x32_bf16 v[92:95], v[156:159], v[212:215], v[92:95]
	v_mfma_f32_16x16x32_bf16 v[92:95], v[152:155], v[208:211], v[92:95]
	s_setprio 0
	s_setprio 1
	v_mfma_f32_16x16x32_bf16 v[76:79], v[168:171], v[208:211], v[76:79]
	v_mfma_f32_16x16x32_bf16 v[76:79], v[172:175], v[212:215], v[76:79]
	v_mfma_f32_16x16x32_bf16 v[116:119], v[172:175], v[188:191], v[116:119]
	v_mfma_f32_16x16x32_bf16 v[116:119], v[168:171], v[184:187], v[116:119]
	v_mfma_f32_16x16x32_bf16 v[112:115], v[176:179], v[184:187], v[112:115]
	v_mfma_f32_16x16x32_bf16 v[112:115], v[180:183], v[188:191], v[112:115]
	v_mfma_f32_16x16x32_bf16 v[96:99], v[180:183], v[196:199], v[96:99]
	v_mfma_f32_16x16x32_bf16 v[96:99], v[176:179], v[192:195], v[96:99]
	v_mfma_f32_16x16x32_bf16 v[100:103], v[168:171], v[192:195], v[100:103]
	v_mfma_f32_16x16x32_bf16 v[100:103], v[172:175], v[196:199], v[100:103]
	v_mfma_f32_16x16x32_bf16 v[84:87], v[172:175], v[204:207], v[84:87]
	v_mfma_f32_16x16x32_bf16 v[84:87], v[168:171], v[200:203], v[84:87]
	v_mfma_f32_16x16x32_bf16 v[80:83], v[176:179], v[200:203], v[80:83]
	v_mfma_f32_16x16x32_bf16 v[80:83], v[180:183], v[204:207], v[80:83]
	v_mfma_f32_16x16x32_bf16 v[72:75], v[180:183], v[212:215], v[72:75]
	v_mfma_f32_16x16x32_bf16 v[72:75], v[176:179], v[208:211], v[72:75]
	s_setprio 0
	s_barrier
	s_add_i32 s68, s68, s24
	s_mov_b32 m0, s68
	ds_read_b128 v[184:187], v150 offset:16384
	ds_read_b128 v[188:191], v150 offset:17408
	ds_read_b128 v[192:195], v150 offset:18432
	ds_read_b128 v[196:199], v150 offset:19456
	ds_read_b128 v[200:203], v150 offset:20480
	ds_read_b128 v[204:207], v150 offset:21504
	ds_read_b128 v[208:211], v150 offset:22528
	ds_read_b128 v[212:215], v150 offset:23552
	global_load_lds_dwordx4 v138, s[18:19]
	s_add_i32 m0, s68, 0x2000
	s_add_u32 s68, s18, 0x4000
	s_addc_u32 s69, s19, 0
	s_add_i32 s88, s88, s24
	global_load_lds_dwordx4 v142, s[18:19]
	s_mov_b32 m0, s88
	s_nop 0
	global_load_lds_dwordx4 v138, s[68:69]
	s_add_i32 m0, s88, 0x2000
	s_nop 0
	global_load_lds_dwordx4 v142, s[68:69]
	s_mov_b32 m0, s27
	s_nop 0
	global_load_lds_dwordx4 v136, s[20:21]
	s_mov_b32 m0, s28
	s_nop 0
	global_load_lds_dwordx4 v140, s[20:21]
	s_waitcnt vmcnt(8)
	s_waitcnt lgkmcnt(0)
	v_mfma_f32_16x16x32_bf16 v[68:71], v[152:155], v[184:187], v[68:71]
	v_mfma_f32_16x16x32_bf16 v[68:71], v[156:159], v[188:191], v[68:71]
	v_mfma_f32_16x16x32_bf16 v[64:67], v[164:167], v[188:191], v[64:67]
	v_mfma_f32_16x16x32_bf16 v[64:67], v[160:163], v[184:187], v[64:67]
	s_barrier
; #define PG8_STAGE(bufoff, gbase, voff) do { _Pragma("unroll") for (int _i = 0; _i < 2; ++_i) \
;         __builtin_amdgcn_global_load_lds((const unsigned*)((const char*)(gbase) + (voff)[_i]), (PG8_LAS unsigned*)(lds + (bufoff) + ldsw + _i * 8192), 16, 0, 0); } while (0)
; #define PG8_LDA(dst, b, h) do { _Pragma("unroll") for (int m = 0; m < 4; ++m) _Pragma("unroll") for (int k = 0; k < 2; ++k) dst[m][k] = *(const PG8_LAS bf16x8*)(lds + PG8_SA(b, h) + aoff + m * 2048 + k * 1024); } while (0)
; #define PG8_LDB(dst, b, h) do { _Pragma("unroll") for (int n = 0; n < 2; ++n) _Pragma("unroll") for (int k = 0; k < 2; ++k) dst[n][k] = *(const PG8_LAS bf16x8*)(lds + PG8_SB(b, h) + boff + n * 2048 + k * 1024); } while (0)
; #define PG8_MMA(ai, bj, At, Bt) do { __builtin_amdgcn_s_setprio(1); _Pragma("unroll") for (int m = 0; m < 4; ++m) _Pragma("unroll") for (int n = 0; n < 2; ++n) _Pragma("unroll") for (int k = 0; k < 2; ++k) \
;         acc[ai][bj][m][n] = __builtin_amdgcn_mfma_f32_16x16x32_bf16(Bt[n][k], At[m][k], acc[ai][bj][m][n], 0, 0, 0); __builtin_amdgcn_s_setprio(0); } while (0)
; #define PG8_WAIT_V(n) asm volatile("s_waitcnt vmcnt(" #n ")" ::: "memory")
; #define PG8_WAIT_L(n) asm volatile("s_waitcnt lgkmcnt(" #n ")" ::: "memory")
; #define PG8_BAR __builtin_amdgcn_s_barrier()
; #define PG8_SCHED __builtin_amdgcn_sched_barrier(0)
; template <class Epi, class Sched, bool ALIGN_EPI = false, bool SP2 = false, bool ABLK = false, bool BBLK = false>
; __device__ __forceinline__ void gemm_phase(PG8_LAS unsigned char* lds, const Gemm g, const Sched& S, const Epi& E) {
;     ...
;             PG8_WAIT_V(8); PG8_WAIT_L(0); PG8_BAR; PG8_MMA(1, 0, At, B0); PG8_MMA(1, 1, At, B1); PG8_BAR; PG8_SCHED;
;             PG8_LDB(B0, 1, 0); PG8_LDB(B1, 1, 1); PG8_SCHED; PG8_LDA(At, 1, 0); PG8_STAGE(PG8_SA(0, 1), a2 + hstepA, voffA);
;             PG8_WAIT_V(8); PG8_WAIT_L(0); PG8_BAR; PG8_MMA(0, 0, At, B0); PG8_MMA(0, 1, At, B1); PG8_BAR; PG8_SCHED;
	s_setprio 1
	v_mfma_f32_16x16x32_bf16 v[56:59], v[160:163], v[192:195], v[56:59]
	v_mfma_f32_16x16x32_bf16 v[56:59], v[164:167], v[196:199], v[56:59]
	v_mfma_f32_16x16x32_bf16 v[60:63], v[156:159], v[196:199], v[60:63]
	v_mfma_f32_16x16x32_bf16 v[60:63], v[152:155], v[192:195], v[60:63]
	v_mfma_f32_16x16x32_bf16 v[44:47], v[152:155], v[200:203], v[44:47]
	v_mfma_f32_16x16x32_bf16 v[44:47], v[156:159], v[204:207], v[44:47]
	v_mfma_f32_16x16x32_bf16 v[40:43], v[164:167], v[204:207], v[40:43]
	v_mfma_f32_16x16x32_bf16 v[40:43], v[160:163], v[200:203], v[40:43]
	v_mfma_f32_16x16x32_bf16 v[20:23], v[160:163], v[208:211], v[20:23]
	v_mfma_f32_16x16x32_bf16 v[20:23], v[164:167], v[212:215], v[20:23]
	v_mfma_f32_16x16x32_bf16 v[24:27], v[156:159], v[212:215], v[24:27]
	v_mfma_f32_16x16x32_bf16 v[24:27], v[152:155], v[208:211], v[24:27]
	s_setprio 0
	s_setprio 1
	v_mfma_f32_16x16x32_bf16 v[8:11], v[168:171], v[208:211], v[8:11]
	v_mfma_f32_16x16x32_bf16 v[8:11], v[172:175], v[212:215], v[8:11]
	v_mfma_f32_16x16x32_bf16 v[52:55], v[172:175], v[188:191], v[52:55]
	v_mfma_f32_16x16x32_bf16 v[52:55], v[168:171], v[184:187], v[52:55]
	v_mfma_f32_16x16x32_bf16 v[48:51], v[176:179], v[184:187], v[48:51]
	v_mfma_f32_16x16x32_bf16 v[48:51], v[180:183], v[188:191], v[48:51]
	v_mfma_f32_16x16x32_bf16 v[28:31], v[180:183], v[196:199], v[28:31]
	v_mfma_f32_16x16x32_bf16 v[28:31], v[176:179], v[192:195], v[28:31]
	v_mfma_f32_16x16x32_bf16 v[32:35], v[168:171], v[192:195], v[32:35]
	v_mfma_f32_16x16x32_bf16 v[32:35], v[172:175], v[196:199], v[32:35]
	v_mfma_f32_16x16x32_bf16 v[16:19], v[172:175], v[204:207], v[16:19]
	v_mfma_f32_16x16x32_bf16 v[16:19], v[168:171], v[200:203], v[16:19]
	v_mfma_f32_16x16x32_bf16 v[12:15], v[176:179], v[200:203], v[12:15]
	v_mfma_f32_16x16x32_bf16 v[12:15], v[180:183], v[204:207], v[12:15]
	v_mfma_f32_16x16x32_bf16 v[4:7], v[180:183], v[212:215], v[4:7]
	v_mfma_f32_16x16x32_bf16 v[4:7], v[176:179], v[208:211], v[4:7]
	s_setprio 0
	s_barrier
	s_add_i32 s68, 0, 0x18000
	v_add_u32_e32 v36, s68, v148
	s_add_i32 s69, 0, 0x1c000
	ds_read_b128 v[152:155], v36
	ds_read_b128 v[156:159], v36 offset:1024
	ds_read_b128 v[160:163], v36 offset:2048
	ds_read_b128 v[164:167], v36 offset:3072
	v_add_u32_e32 v36, s69, v148
	ds_read_b128 v[168:171], v36
	ds_read_b128 v[172:175], v36 offset:1024
	ds_read_b128 v[176:179], v36 offset:2048
	ds_read_b128 v[180:183], v36 offset:3072
	s_add_u32 s20, s20, 0x4000
	s_addc_u32 s21, s21, 0
	s_mov_b32 m0, s29
	ds_read_b128 v[184:187], v150 offset:32768
	ds_read_b128 v[188:191], v150 offset:33792
	ds_read_b128 v[192:195], v150 offset:34816
	ds_read_b128 v[196:199], v150 offset:35840
	ds_read_b128 v[200:203], v150 offset:36864
	ds_read_b128 v[204:207], v150 offset:37888
	ds_read_b128 v[208:211], v150 offset:38912
	ds_read_b128 v[212:215], v150 offset:39936
	global_load_lds_dwordx4 v136, s[20:21]
	s_mov_b32 m0, s30
	s_nop 0
	global_load_lds_dwordx4 v140, s[20:21]
	s_waitcnt vmcnt(8)
	s_waitcnt lgkmcnt(0)
	v_mfma_f32_16x16x32_bf16 v[132:135], v[152:155], v[184:187], v[132:135]
	v_mfma_f32_16x16x32_bf16 v[132:135], v[156:159], v[188:191], v[132:135]
	v_mfma_f32_16x16x32_bf16 v[128:131], v[164:167], v[188:191], v[128:131]
	v_mfma_f32_16x16x32_bf16 v[128:131], v[160:163], v[184:187], v[128:131]
	s_barrier
	s_setprio 1
	v_mfma_f32_16x16x32_bf16 v[120:123], v[160:163], v[192:195], v[120:123]
	v_mfma_f32_16x16x32_bf16 v[120:123], v[164:167], v[196:199], v[120:123]
	v_mfma_f32_16x16x32_bf16 v[124:127], v[156:159], v[196:199], v[124:127]
	v_mfma_f32_16x16x32_bf16 v[124:127], v[152:155], v[192:195], v[124:127]
	v_mfma_f32_16x16x32_bf16 v[108:111], v[152:155], v[200:203], v[108:111]
	v_mfma_f32_16x16x32_bf16 v[108:111], v[156:159], v[204:207], v[108:111]
	v_mfma_f32_16x16x32_bf16 v[104:107], v[164:167], v[204:207], v[104:107]
	v_mfma_f32_16x16x32_bf16 v[104:107], v[160:163], v[200:203], v[104:107]
	v_mfma_f32_16x16x32_bf16 v[88:91], v[160:163], v[208:211], v[88:91]
	v_mfma_f32_16x16x32_bf16 v[88:91], v[164:167], v[212:215], v[88:91]
	v_mfma_f32_16x16x32_bf16 v[92:95], v[156:159], v[212:215], v[92:95]
	v_mfma_f32_16x16x32_bf16 v[92:95], v[152:155], v[208:211], v[92:95]
	s_setprio 0
	s_setprio 1
	v_mfma_f32_16x16x32_bf16 v[76:79], v[168:171], v[208:211], v[76:79]
	v_mfma_f32_16x16x32_bf16 v[76:79], v[172:175], v[212:215], v[76:79]
	v_mfma_f32_16x16x32_bf16 v[116:119], v[172:175], v[188:191], v[116:119]
	v_mfma_f32_16x16x32_bf16 v[116:119], v[168:171], v[184:187], v[116:119]
	v_mfma_f32_16x16x32_bf16 v[112:115], v[176:179], v[184:187], v[112:115]
	v_mfma_f32_16x16x32_bf16 v[112:115], v[180:183], v[188:191], v[112:115]
	v_mfma_f32_16x16x32_bf16 v[96:99], v[180:183], v[196:199], v[96:99]
	v_mfma_f32_16x16x32_bf16 v[96:99], v[176:179], v[192:195], v[96:99]
	v_mfma_f32_16x16x32_bf16 v[100:103], v[168:171], v[192:195], v[100:103]
	v_mfma_f32_16x16x32_bf16 v[100:103], v[172:175], v[196:199], v[100:103]
	v_mfma_f32_16x16x32_bf16 v[84:87], v[172:175], v[204:207], v[84:87]
	v_mfma_f32_16x16x32_bf16 v[84:87], v[168:171], v[200:203], v[84:87]
	v_mfma_f32_16x16x32_bf16 v[80:83], v[176:179], v[200:203], v[80:83]
	v_mfma_f32_16x16x32_bf16 v[80:83], v[180:183], v[204:207], v[80:83]
	v_mfma_f32_16x16x32_bf16 v[72:75], v[180:183], v[212:215], v[72:75]
	v_mfma_f32_16x16x32_bf16 v[72:75], v[176:179], v[208:211], v[72:75]
	s_setprio 0
	s_barrier
; #define PG8_STAGE(bufoff, gbase, voff) do { _Pragma("unroll") for (int _i = 0; _i < 2; ++_i) \
;         __builtin_amdgcn_global_load_lds((const unsigned*)((const char*)(gbase) + (voff)[_i]), (PG8_LAS unsigned*)(lds + (bufoff) + ldsw + _i * 8192), 16, 0, 0); } while (0)
; #define PG8_LDA(dst, b, h) do { _Pragma("unroll") for (int m = 0; m < 4; ++m) _Pragma("unroll") for (int k = 0; k < 2; ++k) dst[m][k] = *(const PG8_LAS bf16x8*)(lds + PG8_SA(b, h) + aoff + m * 2048 + k * 1024); } while (0)
; #define PG8_MMA(ai, bj, At, Bt) do { __builtin_amdgcn_s_setprio(1); _Pragma("unroll") for (int m = 0; m < 4; ++m) _Pragma("unroll") for (int n = 0; n < 2; ++n) _Pragma("unroll") for (int k = 0; k < 2; ++k) \
;         acc[ai][bj][m][n] = __builtin_amdgcn_mfma_f32_16x16x32_bf16(Bt[n][k], At[m][k], acc[ai][bj][m][n], 0, 0, 0); __builtin_amdgcn_s_setprio(0); } while (0)
; #define PG8_WAIT_V(n) asm volatile("s_waitcnt vmcnt(" #n ")" ::: "memory")
; #define PG8_WAIT_L(n) asm volatile("s_waitcnt lgkmcnt(" #n ")" ::: "memory")
; #define PG8_BAR __builtin_amdgcn_s_barrier()
; #define PG8_SCHED __builtin_amdgcn_sched_barrier(0)
; template <class Epi, class Sched, bool ALIGN_EPI = false, bool SP2 = false, bool ABLK = false, bool BBLK = false>
; __device__ __forceinline__ void gemm_phase(PG8_LAS unsigned char* lds, const Gemm g, const Sched& S, const Epi& E) {
;     ...
;             PG8_LDA(At, 1, 1); PG8_STAGE(PG8_SB(1, 0), b3, voffB); PG8_STAGE(PG8_SB(1, 1), b3 + hstepB, voffB); PG8_STAGE(PG8_SA(1, 0), a3, voffA);
;             PG8_WAIT_V(8); PG8_WAIT_L(0); PG8_BAR; PG8_MMA(1, 0, At, B0); PG8_MMA(1, 1, At, B1); PG8_BAR; PG8_SCHED;
;     ...
;         if constexpr (ALIGN_EPI) { if (wr == 0) PG8_BAR; }
	s_add_u32 s20, s18, 0x8000
	s_addc_u32 s21, s19, 0
	s_add_i32 s68, s68, s24
	s_mov_b32 m0, s68
	ds_read_b128 v[184:187], v150 offset:49152
	ds_read_b128 v[188:191], v150 offset:50176
	ds_read_b128 v[192:195], v150 offset:51200
	ds_read_b128 v[196:199], v150 offset:52224
	ds_read_b128 v[200:203], v150 offset:53248
	ds_read_b128 v[204:207], v150 offset:54272
	ds_read_b128 v[208:211], v150 offset:55296
	ds_read_b128 v[212:215], v150 offset:56320
	global_load_lds_dwordx4 v138, s[20:21]
	s_add_i32 m0, s68, 0x2000
	s_add_u32 s18, s18, 0xc000
	s_addc_u32 s19, s19, 0
	global_load_lds_dwordx4 v142, s[20:21]
	s_add_i32 s20, s69, s24
	s_mov_b32 m0, s20
	s_nop 0
	global_load_lds_dwordx4 v138, s[18:19]
	s_add_i32 m0, s20, 0x2000
	s_nop 0
	global_load_lds_dwordx4 v142, s[18:19]
	s_mov_b32 m0, s35
	s_nop 0
	global_load_lds_dwordx4 v136, s[16:17]
	s_mov_b32 m0, s70
	s_nop 0
	global_load_lds_dwordx4 v140, s[16:17]
	s_waitcnt vmcnt(8)
	s_waitcnt lgkmcnt(0)
	v_mfma_f32_16x16x32_bf16 v[68:71], v[152:155], v[184:187], v[68:71]
	v_mfma_f32_16x16x32_bf16 v[68:71], v[156:159], v[188:191], v[68:71]
	v_mfma_f32_16x16x32_bf16 v[64:67], v[164:167], v[188:191], v[64:67]
	v_mfma_f32_16x16x32_bf16 v[64:67], v[160:163], v[184:187], v[64:67]
	s_barrier
	s_setprio 1
	v_mfma_f32_16x16x32_bf16 v[56:59], v[160:163], v[192:195], v[56:59]
	v_mfma_f32_16x16x32_bf16 v[56:59], v[164:167], v[196:199], v[56:59]
	v_mfma_f32_16x16x32_bf16 v[60:63], v[156:159], v[196:199], v[60:63]
	v_mfma_f32_16x16x32_bf16 v[60:63], v[152:155], v[192:195], v[60:63]
	v_mfma_f32_16x16x32_bf16 v[44:47], v[152:155], v[200:203], v[44:47]
	v_mfma_f32_16x16x32_bf16 v[44:47], v[156:159], v[204:207], v[44:47]
	v_mfma_f32_16x16x32_bf16 v[40:43], v[164:167], v[204:207], v[40:43]
	v_mfma_f32_16x16x32_bf16 v[40:43], v[160:163], v[200:203], v[40:43]
	v_mfma_f32_16x16x32_bf16 v[20:23], v[160:163], v[208:211], v[20:23]
	v_mfma_f32_16x16x32_bf16 v[20:23], v[164:167], v[212:215], v[20:23]
	v_mfma_f32_16x16x32_bf16 v[24:27], v[156:159], v[212:215], v[24:27]
	v_mfma_f32_16x16x32_bf16 v[24:27], v[152:155], v[208:211], v[24:27]
	s_setprio 0
	s_setprio 1
	v_mfma_f32_16x16x32_bf16 v[8:11], v[168:171], v[208:211], v[8:11]
	v_mfma_f32_16x16x32_bf16 v[8:11], v[172:175], v[212:215], v[8:11]
	v_mfma_f32_16x16x32_bf16 v[52:55], v[172:175], v[188:191], v[52:55]
	v_mfma_f32_16x16x32_bf16 v[52:55], v[168:171], v[184:187], v[52:55]
	v_mfma_f32_16x16x32_bf16 v[48:51], v[176:179], v[184:187], v[48:51]
	v_mfma_f32_16x16x32_bf16 v[48:51], v[180:183], v[188:191], v[48:51]
	v_mfma_f32_16x16x32_bf16 v[28:31], v[180:183], v[196:199], v[28:31]
	v_mfma_f32_16x16x32_bf16 v[28:31], v[176:179], v[192:195], v[28:31]
	v_mfma_f32_16x16x32_bf16 v[32:35], v[168:171], v[192:195], v[32:35]
	v_mfma_f32_16x16x32_bf16 v[32:35], v[172:175], v[196:199], v[32:35]
	v_mfma_f32_16x16x32_bf16 v[16:19], v[172:175], v[204:207], v[16:19]
	v_mfma_f32_16x16x32_bf16 v[16:19], v[168:171], v[200:203], v[16:19]
	v_mfma_f32_16x16x32_bf16 v[12:15], v[176:179], v[200:203], v[12:15]
	v_mfma_f32_16x16x32_bf16 v[12:15], v[180:183], v[204:207], v[12:15]
	v_mfma_f32_16x16x32_bf16 v[4:7], v[180:183], v[212:215], v[4:7]
	v_mfma_f32_16x16x32_bf16 v[4:7], v[176:179], v[208:211], v[4:7]
	s_setprio 0
	s_barrier
	s_add_i32 s13, s13, 2
	s_add_u32 s10, s10, 0x10000
	s_addc_u32 s11, s11, 0
	s_add_u32 vcc_lo, vcc_lo, 0x10000
	s_addc_u32 vcc_hi, vcc_hi, 0
	s_cmpk_gt_u32 s13, 0x55
	s_cbranch_scc0 .LBB0_439
	s_and_b64 vcc, exec, s[6:7]
	s_cbranch_vccz .LBB0_442
	s_barrier

; #define PG8_STAGE(bufoff, gbase, voff) do { _Pragma("unroll") for (int _i = 0; _i < 2; ++_i) \
;         __builtin_amdgcn_global_load_lds((const unsigned*)((const char*)(gbase) + (voff)[_i]), (PG8_LAS unsigned*)(lds + (bufoff) + ldsw + _i * 8192), 16, 0, 0); } while (0)
; #define PG8_LDA(dst, b, h) do { _Pragma("unroll") for (int m = 0; m < 4; ++m) _Pragma("unroll") for (int k = 0; k < 2; ++k) dst[m][k] = *(const PG8_LAS bf16x8*)(lds + PG8_SA(b, h) + aoff + m * 2048 + k * 1024); } while (0)
; #define PG8_LDB(dst, b, h) do { _Pragma("unroll") for (int n = 0; n < 2; ++n) _Pragma("unroll") for (int k = 0; k < 2; ++k) dst[n][k] = *(const PG8_LAS bf16x8*)(lds + PG8_SB(b, h) + boff + n * 2048 + k * 1024); } while (0)
; #define PG8_MMA(ai, bj, At, Bt) do { __builtin_amdgcn_s_setprio(1); _Pragma("unroll") for (int m = 0; m < 4; ++m) _Pragma("unroll") for (int n = 0; n < 2; ++n) _Pragma("unroll") for (int k = 0; k < 2; ++k) \
;         acc[ai][bj][m][n] = __builtin_amdgcn_mfma_f32_16x16x32_bf16(Bt[n][k], At[m][k], acc[ai][bj][m][n], 0, 0, 0); __builtin_amdgcn_s_setprio(0); } while (0)
; #define PG8_WAIT_V(n) asm volatile("s_waitcnt vmcnt(" #n ")" ::: "memory")
; #define PG8_BAR __builtin_amdgcn_s_barrier()
; template <class Epi, class Sched, bool ALIGN_EPI = false, bool SP2 = false, bool ABLK = false, bool BBLK = false>
; __device__ __forceinline__ void gemm_phase(PG8_LAS unsigned char* lds, const Gemm g, const Sched& S, const Epi& E) {
;     ...
;             const bool last = (t == nt - 2);
;             const char* a1 = cA + (size_t)(t + 1) * kstepA;
;             const char* a2 = last ? nA : cA + (size_t)(t + 2) * kstepA; const char* b2 = last ? nB : cB + (size_t)(t + 2) * kstepB;
;             const char* a3 = a2 + kstepA; const char* b3 = b2 + kstepB;
;             if (last && has_next) S.a_ready(nxt);
;             if constexpr (SP2) {
;             PG8_LDB(B0, 0, 0); PG8_LDB(B1, 0, 1); PG8_SCHED; PG8_LDA(At, 0, 0); PG8_STAGE(PG8_SA(1, 1), a1 + hstepA, voffA);
;             PG8_WAIT_V(8); PG8_WAIT_L(0); PG8_BAR; PG8_MMA(0, 0, At, B0); PG8_MMA(0, 1, At, B1); PG8_BAR; PG8_SCHED;
;             PG8_LDA(At, 0, 1); PG8_STAGE(PG8_SB(0, 0), b2, voffB); PG8_STAGE(PG8_SB(0, 1), b2 + hstepB, voffB); PG8_STAGE(PG8_SA(0, 0), a2, voffA);
;             PG8_WAIT_V(8); PG8_WAIT_L(0); PG8_BAR; PG8_MMA(1, 0, At, B0); PG8_MMA(1, 1, At, B1); PG8_BAR; PG8_SCHED;
.LBB0_916:
	s_add_u32 s22, s20, 0x4000
	s_addc_u32 s23, s21, 0
	s_cmp_eq_u32 s13, 28
	s_cselect_b32 s26, s19, s22
	s_cselect_b32 s27, s1, s23
	s_cselect_b32 s24, s65, s70
	s_cselect_b32 s25, s9, s71
	s_add_u32 s22, s26, 0x8000
	s_addc_u32 s23, s27, 0
	s_add_i32 s68, 0, 0x10000
	v_add_u32_e32 v36, s68, v155
	s_add_i32 s77, 0, 0x14000
	ds_read_b128 v[150:153], v36
	ds_read_b128 v[158:161], v36 offset:1024
	ds_read_b128 v[162:165], v36 offset:2048
	ds_read_b128 v[166:169], v36 offset:3072
	v_add_u32_e32 v36, s77, v155
	ds_read_b128 v[170:173], v36
	ds_read_b128 v[174:177], v36 offset:1024
	ds_read_b128 v[178:181], v36 offset:2048
	ds_read_b128 v[182:185], v36 offset:3072
	s_add_i32 m0, s31, 0xc000
	ds_read_b128 v[186:189], v157
	ds_read_b128 v[190:193], v157 offset:1024
	ds_read_b128 v[194:197], v157 offset:2048
	ds_read_b128 v[198:201], v157 offset:3072
	ds_read_b128 v[202:205], v157 offset:4096
	ds_read_b128 v[206:209], v157 offset:5120
	ds_read_b128 v[210:213], v157 offset:6144
	ds_read_b128 v[214:217], v157 offset:7168
	global_load_lds_dwordx4 v146, s[20:21]
	s_add_i32 m0, s31, 0xe000
	s_nop 0
	global_load_lds_dwordx4 v148, s[20:21]
	s_waitcnt vmcnt(8)
	s_waitcnt lgkmcnt(0)
	v_mfma_f32_16x16x32_bf16 v[132:135], v[150:153], v[186:189], v[132:135]
	v_mfma_f32_16x16x32_bf16 v[132:135], v[158:161], v[190:193], v[132:135]
	v_mfma_f32_16x16x32_bf16 v[128:131], v[166:169], v[190:193], v[128:131]
	v_mfma_f32_16x16x32_bf16 v[128:131], v[162:165], v[186:189], v[128:131]
	s_barrier
	s_setprio 1
	v_mfma_f32_16x16x32_bf16 v[116:119], v[162:165], v[194:197], v[116:119]
	v_mfma_f32_16x16x32_bf16 v[116:119], v[166:169], v[198:201], v[116:119]
	v_mfma_f32_16x16x32_bf16 v[124:127], v[158:161], v[198:201], v[124:127]
	v_mfma_f32_16x16x32_bf16 v[124:127], v[150:153], v[194:197], v[124:127]
	v_mfma_f32_16x16x32_bf16 v[108:111], v[150:153], v[202:205], v[108:111]
	v_mfma_f32_16x16x32_bf16 v[108:111], v[158:161], v[206:209], v[108:111]
	v_mfma_f32_16x16x32_bf16 v[100:103], v[166:169], v[206:209], v[100:103]
	v_mfma_f32_16x16x32_bf16 v[100:103], v[162:165], v[202:205], v[100:103]
	v_mfma_f32_16x16x32_bf16 v[84:87], v[162:165], v[210:213], v[84:87]
	v_mfma_f32_16x16x32_bf16 v[84:87], v[166:169], v[214:217], v[84:87]
	v_mfma_f32_16x16x32_bf16 v[92:95], v[158:161], v[214:217], v[92:95]
	v_mfma_f32_16x16x32_bf16 v[92:95], v[150:153], v[210:213], v[92:95]
	s_setprio 0
	s_setprio 1
	v_mfma_f32_16x16x32_bf16 v[76:79], v[170:173], v[210:213], v[76:79]
	v_mfma_f32_16x16x32_bf16 v[76:79], v[174:177], v[214:217], v[76:79]
	v_mfma_f32_16x16x32_bf16 v[120:123], v[174:177], v[190:193], v[120:123]
	v_mfma_f32_16x16x32_bf16 v[120:123], v[170:173], v[186:189], v[120:123]
	v_mfma_f32_16x16x32_bf16 v[112:115], v[178:181], v[186:189], v[112:115]
	v_mfma_f32_16x16x32_bf16 v[112:115], v[182:185], v[190:193], v[112:115]
	v_mfma_f32_16x16x32_bf16 v[96:99], v[182:185], v[198:201], v[96:99]
	v_mfma_f32_16x16x32_bf16 v[96:99], v[178:181], v[194:197], v[96:99]
	v_mfma_f32_16x16x32_bf16 v[104:107], v[170:173], v[194:197], v[104:107]
	v_mfma_f32_16x16x32_bf16 v[104:107], v[174:177], v[198:201], v[104:107]
	v_mfma_f32_16x16x32_bf16 v[88:91], v[174:177], v[206:209], v[88:91]
	v_mfma_f32_16x16x32_bf16 v[88:91], v[170:173], v[202:205], v[88:91]
	v_mfma_f32_16x16x32_bf16 v[80:83], v[178:181], v[202:205], v[80:83]
	v_mfma_f32_16x16x32_bf16 v[80:83], v[182:185], v[206:209], v[80:83]
	v_mfma_f32_16x16x32_bf16 v[72:75], v[182:185], v[214:217], v[72:75]
	v_mfma_f32_16x16x32_bf16 v[72:75], v[178:181], v[210:213], v[72:75]
	s_setprio 0
	s_barrier
	s_add_i32 s68, s68, s29
	s_mov_b32 m0, s68
	ds_read_b128 v[186:189], v157 offset:16384
	ds_read_b128 v[190:193], v157 offset:17408
	ds_read_b128 v[194:197], v157 offset:18432
	ds_read_b128 v[198:201], v157 offset:19456
	ds_read_b128 v[202:205], v157 offset:20480
	ds_read_b128 v[206:209], v157 offset:21504
	ds_read_b128 v[210:213], v157 offset:22528
	ds_read_b128 v[214:217], v157 offset:23552
	global_load_lds_dwordx4 v140, s[24:25]
	s_add_i32 m0, s68, 0x2000
	s_add_u32 s68, s24, 0x4000
	s_addc_u32 s69, s25, 0
	s_add_i32 s77, s77, s29
	global_load_lds_dwordx4 v136, s[24:25]
	s_mov_b32 m0, s77
	s_nop 0
	global_load_lds_dwordx4 v140, s[68:69]
	s_add_i32 m0, s77, 0x2000
	s_nop 0
	global_load_lds_dwordx4 v136, s[68:69]
	s_mov_b32 m0, s31
	s_nop 0
	global_load_lds_dwordx4 v142, s[26:27]
	s_mov_b32 m0, s34
	s_nop 0
	global_load_lds_dwordx4 v138, s[26:27]
	s_waitcnt vmcnt(8)
	s_waitcnt lgkmcnt(0)
	v_mfma_f32_16x16x32_bf16 v[68:71], v[150:153], v[186:189], v[68:71]
	v_mfma_f32_16x16x32_bf16 v[68:71], v[158:161], v[190:193], v[68:71]
	v_mfma_f32_16x16x32_bf16 v[64:67], v[166:169], v[190:193], v[64:67]
	v_mfma_f32_16x16x32_bf16 v[64:67], v[162:165], v[186:189], v[64:67]
	s_barrier
; #define PG8_STAGE(bufoff, gbase, voff) do { _Pragma("unroll") for (int _i = 0; _i < 2; ++_i) \
;         __builtin_amdgcn_global_load_lds((const unsigned*)((const char*)(gbase) + (voff)[_i]), (PG8_LAS unsigned*)(lds + (bufoff) + ldsw + _i * 8192), 16, 0, 0); } while (0)
; #define PG8_LDA(dst, b, h) do { _Pragma("unroll") for (int m = 0; m < 4; ++m) _Pragma("unroll") for (int k = 0; k < 2; ++k) dst[m][k] = *(const PG8_LAS bf16x8*)(lds + PG8_SA(b, h) + aoff + m * 2048 + k * 1024); } while (0)
; #define PG8_LDB(dst, b, h) do { _Pragma("unroll") for (int n = 0; n < 2; ++n) _Pragma("unroll") for (int k = 0; k < 2; ++k) dst[n][k] = *(const PG8_LAS bf16x8*)(lds + PG8_SB(b, h) + boff + n * 2048 + k * 1024); } while (0)
; #define PG8_MMA(ai, bj, At, Bt) do { __builtin_amdgcn_s_setprio(1); _Pragma("unroll") for (int m = 0; m < 4; ++m) _Pragma("unroll") for (int n = 0; n < 2; ++n) _Pragma("unroll") for (int k = 0; k < 2; ++k) \
;         acc[ai][bj][m][n] = __builtin_amdgcn_mfma_f32_16x16x32_bf16(Bt[n][k], At[m][k], acc[ai][bj][m][n], 0, 0, 0); __builtin_amdgcn_s_setprio(0); } while (0)
; #define PG8_WAIT_V(n) asm volatile("s_waitcnt vmcnt(" #n ")" ::: "memory")
; #define PG8_WAIT_L(n) asm volatile("s_waitcnt lgkmcnt(" #n ")" ::: "memory")
; #define PG8_BAR __builtin_amdgcn_s_barrier()
; #define PG8_SCHED __builtin_amdgcn_sched_barrier(0)
; template <class Epi, class Sched, bool ALIGN_EPI = false, bool SP2 = false, bool ABLK = false, bool BBLK = false>
; __device__ __forceinline__ void gemm_phase(PG8_LAS unsigned char* lds, const Gemm g, const Sched& S, const Epi& E) {
;     ...
;             PG8_WAIT_V(8); PG8_WAIT_L(0); PG8_BAR; PG8_MMA(1, 0, At, B0); PG8_MMA(1, 1, At, B1); PG8_BAR; PG8_SCHED;
;             PG8_LDB(B0, 1, 0); PG8_LDB(B1, 1, 1); PG8_SCHED; PG8_LDA(At, 1, 0); PG8_STAGE(PG8_SA(0, 1), a2 + hstepA, voffA);
;             PG8_WAIT_V(8); PG8_WAIT_L(0); PG8_BAR; PG8_MMA(0, 0, At, B0); PG8_MMA(0, 1, At, B1); PG8_BAR; PG8_SCHED;
	s_setprio 1
	v_mfma_f32_16x16x32_bf16 v[52:55], v[162:165], v[194:197], v[52:55]
	v_mfma_f32_16x16x32_bf16 v[52:55], v[166:169], v[198:201], v[52:55]
	v_mfma_f32_16x16x32_bf16 v[60:63], v[158:161], v[198:201], v[60:63]
	v_mfma_f32_16x16x32_bf16 v[60:63], v[150:153], v[194:197], v[60:63]
	v_mfma_f32_16x16x32_bf16 v[44:47], v[150:153], v[202:205], v[44:47]
	v_mfma_f32_16x16x32_bf16 v[44:47], v[158:161], v[206:209], v[44:47]
	v_mfma_f32_16x16x32_bf16 v[32:35], v[166:169], v[206:209], v[32:35]
	v_mfma_f32_16x16x32_bf16 v[32:35], v[162:165], v[202:205], v[32:35]
	v_mfma_f32_16x16x32_bf16 v[16:19], v[162:165], v[210:213], v[16:19]
	v_mfma_f32_16x16x32_bf16 v[16:19], v[166:169], v[214:217], v[16:19]
	v_mfma_f32_16x16x32_bf16 v[24:27], v[158:161], v[214:217], v[24:27]
	v_mfma_f32_16x16x32_bf16 v[24:27], v[150:153], v[210:213], v[24:27]
	s_setprio 0
	s_setprio 1
	v_mfma_f32_16x16x32_bf16 v[8:11], v[170:173], v[210:213], v[8:11]
	v_mfma_f32_16x16x32_bf16 v[8:11], v[174:177], v[214:217], v[8:11]
	v_mfma_f32_16x16x32_bf16 v[56:59], v[174:177], v[190:193], v[56:59]
	v_mfma_f32_16x16x32_bf16 v[56:59], v[170:173], v[186:189], v[56:59]
	v_mfma_f32_16x16x32_bf16 v[48:51], v[178:181], v[186:189], v[48:51]
	v_mfma_f32_16x16x32_bf16 v[48:51], v[182:185], v[190:193], v[48:51]
	v_mfma_f32_16x16x32_bf16 v[28:31], v[182:185], v[198:201], v[28:31]
	v_mfma_f32_16x16x32_bf16 v[28:31], v[178:181], v[194:197], v[28:31]
	v_mfma_f32_16x16x32_bf16 v[40:43], v[170:173], v[194:197], v[40:43]
	v_mfma_f32_16x16x32_bf16 v[40:43], v[174:177], v[198:201], v[40:43]
	v_mfma_f32_16x16x32_bf16 v[20:23], v[174:177], v[206:209], v[20:23]
	v_mfma_f32_16x16x32_bf16 v[20:23], v[170:173], v[202:205], v[20:23]
	v_mfma_f32_16x16x32_bf16 v[12:15], v[178:181], v[202:205], v[12:15]
	v_mfma_f32_16x16x32_bf16 v[12:15], v[182:185], v[206:209], v[12:15]
	v_mfma_f32_16x16x32_bf16 v[4:7], v[182:185], v[214:217], v[4:7]
	v_mfma_f32_16x16x32_bf16 v[4:7], v[178:181], v[210:213], v[4:7]
	s_setprio 0
	s_barrier
	s_add_i32 s68, 0, 0x18000
	v_add_u32_e32 v36, s68, v155
	s_add_i32 s69, 0, 0x1c000
	ds_read_b128 v[150:153], v36
	ds_read_b128 v[158:161], v36 offset:1024
	ds_read_b128 v[162:165], v36 offset:2048
	ds_read_b128 v[166:169], v36 offset:3072
	v_add_u32_e32 v36, s69, v155
	ds_read_b128 v[170:173], v36
	ds_read_b128 v[174:177], v36 offset:1024
	ds_read_b128 v[178:181], v36 offset:2048
	ds_read_b128 v[182:185], v36 offset:3072
	s_add_u32 s26, s26, 0x4000
	s_addc_u32 s27, s27, 0
	s_mov_b32 m0, s35
	ds_read_b128 v[186:189], v157 offset:32768
	ds_read_b128 v[190:193], v157 offset:33792
	ds_read_b128 v[194:197], v157 offset:34816
	ds_read_b128 v[198:201], v157 offset:35840
	ds_read_b128 v[202:205], v157 offset:36864
	ds_read_b128 v[206:209], v157 offset:37888
	ds_read_b128 v[210:213], v157 offset:38912
	ds_read_b128 v[214:217], v157 offset:39936
	global_load_lds_dwordx4 v142, s[26:27]
	s_mov_b32 m0, s36
	s_nop 0
	global_load_lds_dwordx4 v138, s[26:27]
	s_waitcnt vmcnt(8)
	s_waitcnt lgkmcnt(0)
	v_mfma_f32_16x16x32_bf16 v[132:135], v[150:153], v[186:189], v[132:135]
	v_mfma_f32_16x16x32_bf16 v[132:135], v[158:161], v[190:193], v[132:135]
	v_mfma_f32_16x16x32_bf16 v[128:131], v[166:169], v[190:193], v[128:131]
	v_mfma_f32_16x16x32_bf16 v[128:131], v[162:165], v[186:189], v[128:131]
	s_barrier
	s_setprio 1
	v_mfma_f32_16x16x32_bf16 v[116:119], v[162:165], v[194:197], v[116:119]
	v_mfma_f32_16x16x32_bf16 v[116:119], v[166:169], v[198:201], v[116:119]
	v_mfma_f32_16x16x32_bf16 v[124:127], v[158:161], v[198:201], v[124:127]
	v_mfma_f32_16x16x32_bf16 v[124:127], v[150:153], v[194:197], v[124:127]
	v_mfma_f32_16x16x32_bf16 v[108:111], v[150:153], v[202:205], v[108:111]
	v_mfma_f32_16x16x32_bf16 v[108:111], v[158:161], v[206:209], v[108:111]
	v_mfma_f32_16x16x32_bf16 v[100:103], v[166:169], v[206:209], v[100:103]
	v_mfma_f32_16x16x32_bf16 v[100:103], v[162:165], v[202:205], v[100:103]
	v_mfma_f32_16x16x32_bf16 v[84:87], v[162:165], v[210:213], v[84:87]
	v_mfma_f32_16x16x32_bf16 v[84:87], v[166:169], v[214:217], v[84:87]
	v_mfma_f32_16x16x32_bf16 v[92:95], v[158:161], v[214:217], v[92:95]
	v_mfma_f32_16x16x32_bf16 v[92:95], v[150:153], v[210:213], v[92:95]
	s_setprio 0
	s_setprio 1
	v_mfma_f32_16x16x32_bf16 v[76:79], v[170:173], v[210:213], v[76:79]
	v_mfma_f32_16x16x32_bf16 v[76:79], v[174:177], v[214:217], v[76:79]
	v_mfma_f32_16x16x32_bf16 v[120:123], v[174:177], v[190:193], v[120:123]
	v_mfma_f32_16x16x32_bf16 v[120:123], v[170:173], v[186:189], v[120:123]
	v_mfma_f32_16x16x32_bf16 v[112:115], v[178:181], v[186:189], v[112:115]
	v_mfma_f32_16x16x32_bf16 v[112:115], v[182:185], v[190:193], v[112:115]
	v_mfma_f32_16x16x32_bf16 v[96:99], v[182:185], v[198:201], v[96:99]
	v_mfma_f32_16x16x32_bf16 v[96:99], v[178:181], v[194:197], v[96:99]
	v_mfma_f32_16x16x32_bf16 v[104:107], v[170:173], v[194:197], v[104:107]
	v_mfma_f32_16x16x32_bf16 v[104:107], v[174:177], v[198:201], v[104:107]
	v_mfma_f32_16x16x32_bf16 v[88:91], v[174:177], v[206:209], v[88:91]
	v_mfma_f32_16x16x32_bf16 v[88:91], v[170:173], v[202:205], v[88:91]
	v_mfma_f32_16x16x32_bf16 v[80:83], v[178:181], v[202:205], v[80:83]
	v_mfma_f32_16x16x32_bf16 v[80:83], v[182:185], v[206:209], v[80:83]
	v_mfma_f32_16x16x32_bf16 v[72:75], v[182:185], v[214:217], v[72:75]
	v_mfma_f32_16x16x32_bf16 v[72:75], v[178:181], v[210:213], v[72:75]
	s_setprio 0
	s_barrier
; #define PG8_STAGE(bufoff, gbase, voff) do { _Pragma("unroll") for (int _i = 0; _i < 2; ++_i) \
;         __builtin_amdgcn_global_load_lds((const unsigned*)((const char*)(gbase) + (voff)[_i]), (PG8_LAS unsigned*)(lds + (bufoff) + ldsw + _i * 8192), 16, 0, 0); } while (0)
; #define PG8_LDA(dst, b, h) do { _Pragma("unroll") for (int m = 0; m < 4; ++m) _Pragma("unroll") for (int k = 0; k < 2; ++k) dst[m][k] = *(const PG8_LAS bf16x8*)(lds + PG8_SA(b, h) + aoff + m * 2048 + k * 1024); } while (0)
; #define PG8_MMA(ai, bj, At, Bt) do { __builtin_amdgcn_s_setprio(1); _Pragma("unroll") for (int m = 0; m < 4; ++m) _Pragma("unroll") for (int n = 0; n < 2; ++n) _Pragma("unroll") for (int k = 0; k < 2; ++k) \
;         acc[ai][bj][m][n] = __builtin_amdgcn_mfma_f32_16x16x32_bf16(Bt[n][k], At[m][k], acc[ai][bj][m][n], 0, 0, 0); __builtin_amdgcn_s_setprio(0); } while (0)
; #define PG8_WAIT_V(n) asm volatile("s_waitcnt vmcnt(" #n ")" ::: "memory")
; #define PG8_WAIT_L(n) asm volatile("s_waitcnt lgkmcnt(" #n ")" ::: "memory")
; #define PG8_BAR __builtin_amdgcn_s_barrier()
; #define PG8_SCHED __builtin_amdgcn_sched_barrier(0)
; template <class Epi, class Sched, bool ALIGN_EPI = false, bool SP2 = false, bool ABLK = false, bool BBLK = false>
; __device__ __forceinline__ void gemm_phase(PG8_LAS unsigned char* lds, const Gemm g, const Sched& S, const Epi& E) {
;     ...
;             PG8_LDA(At, 1, 1); PG8_STAGE(PG8_SB(1, 0), b3, voffB); PG8_STAGE(PG8_SB(1, 1), b3 + hstepB, voffB); PG8_STAGE(PG8_SA(1, 0), a3, voffA);
;             PG8_WAIT_V(8); PG8_WAIT_L(0); PG8_BAR; PG8_MMA(1, 0, At, B0); PG8_MMA(1, 1, At, B1); PG8_BAR; PG8_SCHED;
;     ...
;         if constexpr (ALIGN_EPI) { if (wr == 0) PG8_BAR; }
	s_add_u32 s26, s24, 0x8000
	s_addc_u32 s27, s25, 0
	s_add_i32 s68, s68, s29
	s_mov_b32 m0, s68
	ds_read_b128 v[186:189], v157 offset:49152
	ds_read_b128 v[190:193], v157 offset:50176
	ds_read_b128 v[194:197], v157 offset:51200
	ds_read_b128 v[198:201], v157 offset:52224
	ds_read_b128 v[202:205], v157 offset:53248
	ds_read_b128 v[206:209], v157 offset:54272
	ds_read_b128 v[210:213], v157 offset:55296
	ds_read_b128 v[214:217], v157 offset:56320
	global_load_lds_dwordx4 v140, s[26:27]
	s_add_i32 m0, s68, 0x2000
	s_add_u32 s24, s24, 0xc000
	s_addc_u32 s25, s25, 0
	global_load_lds_dwordx4 v136, s[26:27]
	s_add_i32 s26, s69, s29
	s_mov_b32 m0, s26
	s_nop 0
	global_load_lds_dwordx4 v140, s[24:25]
	s_add_i32 m0, s26, 0x2000
	s_nop 0
	global_load_lds_dwordx4 v136, s[24:25]
	s_mov_b32 m0, s37
	s_nop 0
	global_load_lds_dwordx4 v142, s[22:23]
	s_mov_b32 m0, s62
	s_nop 0
	global_load_lds_dwordx4 v138, s[22:23]
	s_waitcnt vmcnt(8)
	s_waitcnt lgkmcnt(0)
	v_mfma_f32_16x16x32_bf16 v[68:71], v[150:153], v[186:189], v[68:71]
	v_mfma_f32_16x16x32_bf16 v[68:71], v[158:161], v[190:193], v[68:71]
	v_mfma_f32_16x16x32_bf16 v[64:67], v[166:169], v[190:193], v[64:67]
	v_mfma_f32_16x16x32_bf16 v[64:67], v[162:165], v[186:189], v[64:67]
	s_barrier
	s_setprio 1
	v_mfma_f32_16x16x32_bf16 v[52:55], v[162:165], v[194:197], v[52:55]
	v_mfma_f32_16x16x32_bf16 v[52:55], v[166:169], v[198:201], v[52:55]
	v_mfma_f32_16x16x32_bf16 v[60:63], v[158:161], v[198:201], v[60:63]
	v_mfma_f32_16x16x32_bf16 v[60:63], v[150:153], v[194:197], v[60:63]
	v_mfma_f32_16x16x32_bf16 v[44:47], v[150:153], v[202:205], v[44:47]
	v_mfma_f32_16x16x32_bf16 v[44:47], v[158:161], v[206:209], v[44:47]
	v_mfma_f32_16x16x32_bf16 v[32:35], v[166:169], v[206:209], v[32:35]
	v_mfma_f32_16x16x32_bf16 v[32:35], v[162:165], v[202:205], v[32:35]
	v_mfma_f32_16x16x32_bf16 v[16:19], v[162:165], v[210:213], v[16:19]
	v_mfma_f32_16x16x32_bf16 v[16:19], v[166:169], v[214:217], v[16:19]
	v_mfma_f32_16x16x32_bf16 v[24:27], v[158:161], v[214:217], v[24:27]
	v_mfma_f32_16x16x32_bf16 v[24:27], v[150:153], v[210:213], v[24:27]
	s_setprio 0
	s_setprio 1
	v_mfma_f32_16x16x32_bf16 v[8:11], v[170:173], v[210:213], v[8:11]
	v_mfma_f32_16x16x32_bf16 v[8:11], v[174:177], v[214:217], v[8:11]
	v_mfma_f32_16x16x32_bf16 v[56:59], v[174:177], v[190:193], v[56:59]
	v_mfma_f32_16x16x32_bf16 v[56:59], v[170:173], v[186:189], v[56:59]
	v_mfma_f32_16x16x32_bf16 v[48:51], v[178:181], v[186:189], v[48:51]
	v_mfma_f32_16x16x32_bf16 v[48:51], v[182:185], v[190:193], v[48:51]
	v_mfma_f32_16x16x32_bf16 v[28:31], v[182:185], v[198:201], v[28:31]
	v_mfma_f32_16x16x32_bf16 v[28:31], v[178:181], v[194:197], v[28:31]
	v_mfma_f32_16x16x32_bf16 v[40:43], v[170:173], v[194:197], v[40:43]
	v_mfma_f32_16x16x32_bf16 v[40:43], v[174:177], v[198:201], v[40:43]
	v_mfma_f32_16x16x32_bf16 v[20:23], v[174:177], v[206:209], v[20:23]
	v_mfma_f32_16x16x32_bf16 v[20:23], v[170:173], v[202:205], v[20:23]
	v_mfma_f32_16x16x32_bf16 v[12:15], v[178:181], v[202:205], v[12:15]
	v_mfma_f32_16x16x32_bf16 v[12:15], v[182:185], v[206:209], v[12:15]
	v_mfma_f32_16x16x32_bf16 v[4:7], v[182:185], v[214:217], v[4:7]
	v_mfma_f32_16x16x32_bf16 v[4:7], v[178:181], v[210:213], v[4:7]
	s_setprio 0
	s_barrier
	s_add_i32 s13, s13, 2
	s_add_u32 s20, s20, 0x10000
	s_addc_u32 s21, s21, 0
	s_add_u32 s70, s70, 0x10000
	s_addc_u32 s71, s71, 0
	s_cmp_gt_u32 s13, 29
	s_cbranch_scc0 .LBB0_916
	s_and_b64 vcc, exec, s[6:7]
	s_cbranch_vccz .LBB0_919
	s_barrier

; #define PG8_STAGE(bufoff, gbase, voff) do { _Pragma("unroll") for (int _i = 0; _i < 2; ++_i) \
;         __builtin_amdgcn_global_load_lds((const unsigned*)((const char*)(gbase) + (voff)[_i]), (PG8_LAS unsigned*)(lds + (bufoff) + ldsw + _i * 8192), 16, 0, 0); } while (0)
; #define PG8_LDA(dst, b, h) do { _Pragma("unroll") for (int m = 0; m < 4; ++m) _Pragma("unroll") for (int k = 0; k < 2; ++k) dst[m][k] = *(const PG8_LAS bf16x8*)(lds + PG8_SA(b, h) + aoff + m * 2048 + k * 1024); } while (0)
; #define PG8_LDB(dst, b, h) do { _Pragma("unroll") for (int n = 0; n < 2; ++n) _Pragma("unroll") for (int k = 0; k < 2; ++k) dst[n][k] = *(const PG8_LAS bf16x8*)(lds + PG8_SB(b, h) + boff + n * 2048 + k * 1024); } while (0)
; #define PG8_MMA(ai, bj, At, Bt) do { __builtin_amdgcn_s_setprio(1); _Pragma("unroll") for (int m = 0; m < 4; ++m) _Pragma("unroll") for (int n = 0; n < 2; ++n) _Pragma("unroll") for (int k = 0; k < 2; ++k) \
;         acc[ai][bj][m][n] = __builtin_amdgcn_mfma_f32_16x16x32_bf16(Bt[n][k], At[m][k], acc[ai][bj][m][n], 0, 0, 0); __builtin_amdgcn_s_setprio(0); } while (0)
; #define PG8_WAIT_V(n) asm volatile("s_waitcnt vmcnt(" #n ")" ::: "memory")
; #define PG8_BAR __builtin_amdgcn_s_barrier()
; template <class Epi, class Sched, bool ALIGN_EPI = false, bool SP2 = false, bool ABLK = false, bool BBLK = false>
; __device__ __forceinline__ void gemm_phase(PG8_LAS unsigned char* lds, const Gemm g, const Sched& S, const Epi& E) {
;     ...
;             const bool last = (t == nt - 2);
;             const char* a1 = cA + (size_t)(t + 1) * kstepA;
;             const char* a2 = last ? nA : cA + (size_t)(t + 2) * kstepA; const char* b2 = last ? nB : cB + (size_t)(t + 2) * kstepB;
;             const char* a3 = a2 + kstepA; const char* b3 = b2 + kstepB;
;             if (last && has_next) S.a_ready(nxt);
;             if constexpr (SP2) {
;             PG8_LDB(B0, 0, 0); PG8_LDB(B1, 0, 1); PG8_SCHED; PG8_LDA(At, 0, 0); PG8_STAGE(PG8_SA(1, 1), a1 + hstepA, voffA);
;             PG8_WAIT_V(8); PG8_WAIT_L(0); PG8_BAR; PG8_MMA(0, 0, At, B0); PG8_MMA(0, 1, At, B1); PG8_BAR; PG8_SCHED;
;             PG8_LDA(At, 0, 1); PG8_STAGE(PG8_SB(0, 0), b2, voffB); PG8_STAGE(PG8_SB(0, 1), b2 + hstepB, voffB); PG8_STAGE(PG8_SA(0, 0), a2, voffA);
;             PG8_WAIT_V(8); PG8_WAIT_L(0); PG8_BAR; PG8_MMA(1, 0, At, B0); PG8_MMA(1, 1, At, B1); PG8_BAR; PG8_SCHED;
.LBB0_2111:
	s_add_u32 s24, s22, 0x4000
	s_addc_u32 s25, s23, 0
	s_cmp_eq_u32 s13, 28
	s_cselect_b32 s28, s17, s24
	s_cselect_b32 s29, s12, s25
	s_cselect_b32 s26, s77, s82
	s_cselect_b32 s27, s11, vcc_lo
	s_add_u32 s24, s28, 0x8000
	s_addc_u32 s25, s29, 0
	s_add_i32 s68, 0, 0x10000
	v_add_u32_e32 v151, s68, v148
	s_add_i32 s88, 0, 0x14000
	ds_read_b128 v[36:39], v151
	ds_read_b128 v[152:155], v151 offset:1024
	ds_read_b128 v[156:159], v151 offset:2048
	ds_read_b128 v[160:163], v151 offset:3072
	v_add_u32_e32 v151, s88, v148
	ds_read_b128 v[164:167], v151
	ds_read_b128 v[168:171], v151 offset:1024
	ds_read_b128 v[172:175], v151 offset:2048
	ds_read_b128 v[176:179], v151 offset:3072
	s_add_i32 m0, s9, 0xc000
	ds_read_b128 v[180:183], v150
	ds_read_b128 v[184:187], v150 offset:1024
	ds_read_b128 v[188:191], v150 offset:2048
	ds_read_b128 v[192:195], v150 offset:3072
	ds_read_b128 v[196:199], v150 offset:4096
	ds_read_b128 v[200:203], v150 offset:5120
	ds_read_b128 v[204:207], v150 offset:6144
	ds_read_b128 v[208:211], v150 offset:7168
	global_load_lds_dwordx4 v144, s[22:23]
	s_add_i32 m0, s9, 0xe000
	s_nop 0
	global_load_lds_dwordx4 v146, s[22:23]
	s_waitcnt vmcnt(8)
	s_waitcnt lgkmcnt(0)
	v_mfma_f32_16x16x32_bf16 v[132:135], v[36:39], v[180:183], v[132:135]
	v_mfma_f32_16x16x32_bf16 v[132:135], v[152:155], v[184:187], v[132:135]
	v_mfma_f32_16x16x32_bf16 v[128:131], v[160:163], v[184:187], v[128:131]
	v_mfma_f32_16x16x32_bf16 v[128:131], v[156:159], v[180:183], v[128:131]
	s_barrier
	s_setprio 1
	v_mfma_f32_16x16x32_bf16 v[120:123], v[156:159], v[188:191], v[120:123]
	v_mfma_f32_16x16x32_bf16 v[120:123], v[160:163], v[192:195], v[120:123]
	v_mfma_f32_16x16x32_bf16 v[124:127], v[152:155], v[192:195], v[124:127]
	v_mfma_f32_16x16x32_bf16 v[124:127], v[36:39], v[188:191], v[124:127]
	v_mfma_f32_16x16x32_bf16 v[108:111], v[36:39], v[196:199], v[108:111]
	v_mfma_f32_16x16x32_bf16 v[108:111], v[152:155], v[200:203], v[108:111]
	v_mfma_f32_16x16x32_bf16 v[104:107], v[160:163], v[200:203], v[104:107]
	v_mfma_f32_16x16x32_bf16 v[104:107], v[156:159], v[196:199], v[104:107]
	v_mfma_f32_16x16x32_bf16 v[88:91], v[156:159], v[204:207], v[88:91]
	v_mfma_f32_16x16x32_bf16 v[88:91], v[160:163], v[208:211], v[88:91]
	v_mfma_f32_16x16x32_bf16 v[92:95], v[152:155], v[208:211], v[92:95]
	v_mfma_f32_16x16x32_bf16 v[92:95], v[36:39], v[204:207], v[92:95]
	s_setprio 0
	s_setprio 1
	v_mfma_f32_16x16x32_bf16 v[76:79], v[164:167], v[204:207], v[76:79]
	v_mfma_f32_16x16x32_bf16 v[76:79], v[168:171], v[208:211], v[76:79]
	v_mfma_f32_16x16x32_bf16 v[116:119], v[168:171], v[184:187], v[116:119]
	v_mfma_f32_16x16x32_bf16 v[116:119], v[164:167], v[180:183], v[116:119]
	v_mfma_f32_16x16x32_bf16 v[112:115], v[172:175], v[180:183], v[112:115]
	v_mfma_f32_16x16x32_bf16 v[112:115], v[176:179], v[184:187], v[112:115]
	v_mfma_f32_16x16x32_bf16 v[96:99], v[176:179], v[192:195], v[96:99]
	v_mfma_f32_16x16x32_bf16 v[96:99], v[172:175], v[188:191], v[96:99]
	v_mfma_f32_16x16x32_bf16 v[100:103], v[164:167], v[188:191], v[100:103]
	v_mfma_f32_16x16x32_bf16 v[100:103], v[168:171], v[192:195], v[100:103]
	v_mfma_f32_16x16x32_bf16 v[84:87], v[168:171], v[200:203], v[84:87]
	v_mfma_f32_16x16x32_bf16 v[84:87], v[164:167], v[196:199], v[84:87]
	v_mfma_f32_16x16x32_bf16 v[80:83], v[172:175], v[196:199], v[80:83]
	v_mfma_f32_16x16x32_bf16 v[80:83], v[176:179], v[200:203], v[80:83]
	v_mfma_f32_16x16x32_bf16 v[72:75], v[176:179], v[208:211], v[72:75]
	v_mfma_f32_16x16x32_bf16 v[72:75], v[172:175], v[204:207], v[72:75]
	s_setprio 0
	s_barrier
	s_add_i32 s68, s68, s34
	s_mov_b32 m0, s68
	ds_read_b128 v[180:183], v150 offset:16384
	ds_read_b128 v[184:187], v150 offset:17408
	ds_read_b128 v[188:191], v150 offset:18432
	ds_read_b128 v[192:195], v150 offset:19456
	ds_read_b128 v[196:199], v150 offset:20480
	ds_read_b128 v[200:203], v150 offset:21504
	ds_read_b128 v[204:207], v150 offset:22528
	ds_read_b128 v[208:211], v150 offset:23552
	global_load_lds_dwordx4 v138, s[26:27]
	s_add_i32 m0, s68, 0x2000
	s_add_u32 s68, s26, 0x4000
	s_addc_u32 s69, s27, 0
	s_add_i32 s88, s88, s34
	global_load_lds_dwordx4 v142, s[26:27]
	s_mov_b32 m0, s88
	s_nop 0
	global_load_lds_dwordx4 v138, s[68:69]
	s_add_i32 m0, s88, 0x2000
	s_nop 0
	global_load_lds_dwordx4 v142, s[68:69]
	s_mov_b32 m0, s9
	s_nop 0
	global_load_lds_dwordx4 v136, s[28:29]
	s_mov_b32 m0, s35
	s_nop 0
	global_load_lds_dwordx4 v140, s[28:29]
	s_waitcnt vmcnt(8)
	s_waitcnt lgkmcnt(0)
	v_mfma_f32_16x16x32_bf16 v[68:71], v[36:39], v[180:183], v[68:71]
	v_mfma_f32_16x16x32_bf16 v[68:71], v[152:155], v[184:187], v[68:71]
	v_mfma_f32_16x16x32_bf16 v[64:67], v[160:163], v[184:187], v[64:67]
	v_mfma_f32_16x16x32_bf16 v[64:67], v[156:159], v[180:183], v[64:67]
	s_barrier
; #define PG8_STAGE(bufoff, gbase, voff) do { _Pragma("unroll") for (int _i = 0; _i < 2; ++_i) \
;         __builtin_amdgcn_global_load_lds((const unsigned*)((const char*)(gbase) + (voff)[_i]), (PG8_LAS unsigned*)(lds + (bufoff) + ldsw + _i * 8192), 16, 0, 0); } while (0)
; #define PG8_LDA(dst, b, h) do { _Pragma("unroll") for (int m = 0; m < 4; ++m) _Pragma("unroll") for (int k = 0; k < 2; ++k) dst[m][k] = *(const PG8_LAS bf16x8*)(lds + PG8_SA(b, h) + aoff + m * 2048 + k * 1024); } while (0)
; #define PG8_LDB(dst, b, h) do { _Pragma("unroll") for (int n = 0; n < 2; ++n) _Pragma("unroll") for (int k = 0; k < 2; ++k) dst[n][k] = *(const PG8_LAS bf16x8*)(lds + PG8_SB(b, h) + boff + n * 2048 + k * 1024); } while (0)
; #define PG8_MMA(ai, bj, At, Bt) do { __builtin_amdgcn_s_setprio(1); _Pragma("unroll") for (int m = 0; m < 4; ++m) _Pragma("unroll") for (int n = 0; n < 2; ++n) _Pragma("unroll") for (int k = 0; k < 2; ++k) \
;         acc[ai][bj][m][n] = __builtin_amdgcn_mfma_f32_16x16x32_bf16(Bt[n][k], At[m][k], acc[ai][bj][m][n], 0, 0, 0); __builtin_amdgcn_s_setprio(0); } while (0)
; #define PG8_WAIT_V(n) asm volatile("s_waitcnt vmcnt(" #n ")" ::: "memory")
; #define PG8_WAIT_L(n) asm volatile("s_waitcnt lgkmcnt(" #n ")" ::: "memory")
; #define PG8_BAR __builtin_amdgcn_s_barrier()
; #define PG8_SCHED __builtin_amdgcn_sched_barrier(0)
; template <class Epi, class Sched, bool ALIGN_EPI = false, bool SP2 = false, bool ABLK = false, bool BBLK = false>
; __device__ __forceinline__ void gemm_phase(PG8_LAS unsigned char* lds, const Gemm g, const Sched& S, const Epi& E) {
;     ...
;             PG8_WAIT_V(8); PG8_WAIT_L(0); PG8_BAR; PG8_MMA(1, 0, At, B0); PG8_MMA(1, 1, At, B1); PG8_BAR; PG8_SCHED;
;             PG8_LDB(B0, 1, 0); PG8_LDB(B1, 1, 1); PG8_SCHED; PG8_LDA(At, 1, 0); PG8_STAGE(PG8_SA(0, 1), a2 + hstepA, voffA);
;             PG8_WAIT_V(8); PG8_WAIT_L(0); PG8_BAR; PG8_MMA(0, 0, At, B0); PG8_MMA(0, 1, At, B1); PG8_BAR; PG8_SCHED;
	s_setprio 1
	v_mfma_f32_16x16x32_bf16 v[56:59], v[156:159], v[188:191], v[56:59]
	v_mfma_f32_16x16x32_bf16 v[56:59], v[160:163], v[192:195], v[56:59]
	v_mfma_f32_16x16x32_bf16 v[60:63], v[152:155], v[192:195], v[60:63]
	v_mfma_f32_16x16x32_bf16 v[60:63], v[36:39], v[188:191], v[60:63]
	v_mfma_f32_16x16x32_bf16 v[44:47], v[36:39], v[196:199], v[44:47]
	v_mfma_f32_16x16x32_bf16 v[44:47], v[152:155], v[200:203], v[44:47]
	v_mfma_f32_16x16x32_bf16 v[40:43], v[160:163], v[200:203], v[40:43]
	v_mfma_f32_16x16x32_bf16 v[40:43], v[156:159], v[196:199], v[40:43]
	v_mfma_f32_16x16x32_bf16 v[20:23], v[156:159], v[204:207], v[20:23]
	v_mfma_f32_16x16x32_bf16 v[20:23], v[160:163], v[208:211], v[20:23]
	v_mfma_f32_16x16x32_bf16 v[24:27], v[152:155], v[208:211], v[24:27]
	v_mfma_f32_16x16x32_bf16 v[24:27], v[36:39], v[204:207], v[24:27]
	s_setprio 0
	s_setprio 1
	v_mfma_f32_16x16x32_bf16 v[48:51], v[172:175], v[180:183], v[48:51]
	v_mfma_f32_16x16x32_bf16 v[32:35], v[164:167], v[188:191], v[32:35]
	v_mfma_f32_16x16x32_bf16 v[28:31], v[172:175], v[188:191], v[28:31]
	v_mfma_f32_16x16x32_bf16 v[16:19], v[164:167], v[196:199], v[16:19]
	v_mfma_f32_16x16x32_bf16 v[12:15], v[172:175], v[196:199], v[12:15]
	v_mfma_f32_16x16x32_bf16 v[8:11], v[164:167], v[204:207], v[8:11]
	v_mfma_f32_16x16x32_bf16 v[4:7], v[172:175], v[204:207], v[4:7]
	v_mfma_f32_16x16x32_bf16 v[36:39], v[164:167], v[180:183], v[52:55]
	v_mfma_f32_16x16x32_bf16 v[48:51], v[176:179], v[184:187], v[48:51]
	v_mfma_f32_16x16x32_bf16 v[32:35], v[168:171], v[192:195], v[32:35]
	v_mfma_f32_16x16x32_bf16 v[28:31], v[176:179], v[192:195], v[28:31]
	v_mfma_f32_16x16x32_bf16 v[16:19], v[168:171], v[200:203], v[16:19]
	v_mfma_f32_16x16x32_bf16 v[12:15], v[176:179], v[200:203], v[12:15]
	v_mfma_f32_16x16x32_bf16 v[8:11], v[168:171], v[208:211], v[8:11]
	v_mfma_f32_16x16x32_bf16 v[4:7], v[176:179], v[208:211], v[4:7]
	v_mfma_f32_16x16x32_bf16 v[36:39], v[168:171], v[184:187], v[36:39]
	s_setprio 0
	s_barrier
	s_add_i32 s68, 0, 0x18000
	v_add_u32_e32 v151, s68, v148
	s_add_i32 s69, 0, 0x1c000
	ds_read_b128 v[52:55], v151
	ds_read_b128 v[152:155], v151 offset:1024
	ds_read_b128 v[156:159], v151 offset:2048
	ds_read_b128 v[160:163], v151 offset:3072
	v_add_u32_e32 v151, s69, v148
	ds_read_b128 v[164:167], v151
	ds_read_b128 v[168:171], v151 offset:1024
	ds_read_b128 v[172:175], v151 offset:2048
	ds_read_b128 v[176:179], v151 offset:3072
	s_add_u32 s28, s28, 0x4000
	s_addc_u32 s29, s29, 0
	s_mov_b32 m0, s36
	ds_read_b128 v[180:183], v150 offset:32768
	ds_read_b128 v[184:187], v150 offset:33792
	ds_read_b128 v[188:191], v150 offset:34816
	ds_read_b128 v[192:195], v150 offset:35840
	ds_read_b128 v[196:199], v150 offset:36864
	ds_read_b128 v[200:203], v150 offset:37888
	ds_read_b128 v[204:207], v150 offset:38912
	ds_read_b128 v[208:211], v150 offset:39936
	global_load_lds_dwordx4 v136, s[28:29]
	s_mov_b32 m0, s37
	s_nop 0
	global_load_lds_dwordx4 v140, s[28:29]
	s_waitcnt vmcnt(8)
	s_waitcnt lgkmcnt(0)
	v_mfma_f32_16x16x32_bf16 v[132:135], v[52:55], v[180:183], v[132:135]
	v_mfma_f32_16x16x32_bf16 v[132:135], v[152:155], v[184:187], v[132:135]
	v_mfma_f32_16x16x32_bf16 v[128:131], v[160:163], v[184:187], v[128:131]
	v_mfma_f32_16x16x32_bf16 v[128:131], v[156:159], v[180:183], v[128:131]
	s_barrier
	s_setprio 1
	v_mfma_f32_16x16x32_bf16 v[120:123], v[156:159], v[188:191], v[120:123]
	v_mfma_f32_16x16x32_bf16 v[120:123], v[160:163], v[192:195], v[120:123]
	v_mfma_f32_16x16x32_bf16 v[124:127], v[152:155], v[192:195], v[124:127]
	v_mfma_f32_16x16x32_bf16 v[124:127], v[52:55], v[188:191], v[124:127]
	v_mfma_f32_16x16x32_bf16 v[108:111], v[52:55], v[196:199], v[108:111]
	v_mfma_f32_16x16x32_bf16 v[108:111], v[152:155], v[200:203], v[108:111]
	v_mfma_f32_16x16x32_bf16 v[104:107], v[160:163], v[200:203], v[104:107]
	v_mfma_f32_16x16x32_bf16 v[104:107], v[156:159], v[196:199], v[104:107]
	v_mfma_f32_16x16x32_bf16 v[88:91], v[156:159], v[204:207], v[88:91]
	v_mfma_f32_16x16x32_bf16 v[88:91], v[160:163], v[208:211], v[88:91]
	v_mfma_f32_16x16x32_bf16 v[92:95], v[152:155], v[208:211], v[92:95]
	v_mfma_f32_16x16x32_bf16 v[92:95], v[52:55], v[204:207], v[92:95]
	s_setprio 0
	s_setprio 1
	v_mfma_f32_16x16x32_bf16 v[76:79], v[164:167], v[204:207], v[76:79]
	v_mfma_f32_16x16x32_bf16 v[76:79], v[168:171], v[208:211], v[76:79]
	v_mfma_f32_16x16x32_bf16 v[116:119], v[168:171], v[184:187], v[116:119]
	v_mfma_f32_16x16x32_bf16 v[116:119], v[164:167], v[180:183], v[116:119]
	v_mfma_f32_16x16x32_bf16 v[112:115], v[172:175], v[180:183], v[112:115]
	v_mfma_f32_16x16x32_bf16 v[112:115], v[176:179], v[184:187], v[112:115]
	v_mfma_f32_16x16x32_bf16 v[96:99], v[176:179], v[192:195], v[96:99]
	v_mfma_f32_16x16x32_bf16 v[96:99], v[172:175], v[188:191], v[96:99]
	v_mfma_f32_16x16x32_bf16 v[100:103], v[164:167], v[188:191], v[100:103]
	v_mfma_f32_16x16x32_bf16 v[100:103], v[168:171], v[192:195], v[100:103]
	v_mfma_f32_16x16x32_bf16 v[84:87], v[168:171], v[200:203], v[84:87]
	v_mfma_f32_16x16x32_bf16 v[84:87], v[164:167], v[196:199], v[84:87]
	v_mfma_f32_16x16x32_bf16 v[80:83], v[172:175], v[196:199], v[80:83]
	v_mfma_f32_16x16x32_bf16 v[80:83], v[176:179], v[200:203], v[80:83]
	v_mfma_f32_16x16x32_bf16 v[72:75], v[176:179], v[208:211], v[72:75]
	v_mfma_f32_16x16x32_bf16 v[72:75], v[172:175], v[204:207], v[72:75]
	s_setprio 0
	s_barrier
; #define PG8_STAGE(bufoff, gbase, voff) do { _Pragma("unroll") for (int _i = 0; _i < 2; ++_i) \
;         __builtin_amdgcn_global_load_lds((const unsigned*)((const char*)(gbase) + (voff)[_i]), (PG8_LAS unsigned*)(lds + (bufoff) + ldsw + _i * 8192), 16, 0, 0); } while (0)
; #define PG8_LDA(dst, b, h) do { _Pragma("unroll") for (int m = 0; m < 4; ++m) _Pragma("unroll") for (int k = 0; k < 2; ++k) dst[m][k] = *(const PG8_LAS bf16x8*)(lds + PG8_SA(b, h) + aoff + m * 2048 + k * 1024); } while (0)
; #define PG8_MMA(ai, bj, At, Bt) do { __builtin_amdgcn_s_setprio(1); _Pragma("unroll") for (int m = 0; m < 4; ++m) _Pragma("unroll") for (int n = 0; n < 2; ++n) _Pragma("unroll") for (int k = 0; k < 2; ++k) \
;         acc[ai][bj][m][n] = __builtin_amdgcn_mfma_f32_16x16x32_bf16(Bt[n][k], At[m][k], acc[ai][bj][m][n], 0, 0, 0); __builtin_amdgcn_s_setprio(0); } while (0)
; #define PG8_WAIT_V(n) asm volatile("s_waitcnt vmcnt(" #n ")" ::: "memory")
; #define PG8_WAIT_L(n) asm volatile("s_waitcnt lgkmcnt(" #n ")" ::: "memory")
; #define PG8_BAR __builtin_amdgcn_s_barrier()
; #define PG8_SCHED __builtin_amdgcn_sched_barrier(0)
; template <class Epi, class Sched, bool ALIGN_EPI = false, bool SP2 = false, bool ABLK = false, bool BBLK = false>
; __device__ __forceinline__ void gemm_phase(PG8_LAS unsigned char* lds, const Gemm g, const Sched& S, const Epi& E) {
;     ...
;             PG8_LDA(At, 1, 1); PG8_STAGE(PG8_SB(1, 0), b3, voffB); PG8_STAGE(PG8_SB(1, 1), b3 + hstepB, voffB); PG8_STAGE(PG8_SA(1, 0), a3, voffA);
;             PG8_WAIT_V(8); PG8_WAIT_L(0); PG8_BAR; PG8_MMA(1, 0, At, B0); PG8_MMA(1, 1, At, B1); PG8_BAR; PG8_SCHED;
;     ...
;         if constexpr (ALIGN_EPI) { if (wr == 0) PG8_BAR; }
	s_add_u32 s28, s26, 0x8000
	s_addc_u32 s29, s27, 0
	s_add_i32 s68, s68, s34
	s_mov_b32 m0, s68
	ds_read_b128 v[180:183], v150 offset:49152
	ds_read_b128 v[184:187], v150 offset:50176
	ds_read_b128 v[188:191], v150 offset:51200
	ds_read_b128 v[192:195], v150 offset:52224
	ds_read_b128 v[196:199], v150 offset:53248
	ds_read_b128 v[200:203], v150 offset:54272
	ds_read_b128 v[204:207], v150 offset:55296
	ds_read_b128 v[208:211], v150 offset:56320
	global_load_lds_dwordx4 v138, s[28:29]
	s_add_i32 m0, s68, 0x2000
	s_add_u32 s26, s26, 0xc000
	s_addc_u32 s27, s27, 0
	global_load_lds_dwordx4 v142, s[28:29]
	s_add_i32 s28, s69, s34
	s_mov_b32 m0, s28
	s_nop 0
	global_load_lds_dwordx4 v138, s[26:27]
	s_add_i32 m0, s28, 0x2000
	s_nop 0
	global_load_lds_dwordx4 v142, s[26:27]
	s_mov_b32 m0, s64
	s_nop 0
	global_load_lds_dwordx4 v136, s[24:25]
	s_mov_b32 m0, s65
	s_nop 0
	global_load_lds_dwordx4 v140, s[24:25]
	s_waitcnt vmcnt(8)
	s_waitcnt lgkmcnt(0)
	v_mfma_f32_16x16x32_bf16 v[68:71], v[52:55], v[180:183], v[68:71]
	v_mfma_f32_16x16x32_bf16 v[68:71], v[152:155], v[184:187], v[68:71]
	v_mfma_f32_16x16x32_bf16 v[64:67], v[160:163], v[184:187], v[64:67]
	v_mfma_f32_16x16x32_bf16 v[64:67], v[156:159], v[180:183], v[64:67]
	s_barrier
	s_setprio 1
	v_mfma_f32_16x16x32_bf16 v[56:59], v[156:159], v[188:191], v[56:59]
	v_mfma_f32_16x16x32_bf16 v[56:59], v[160:163], v[192:195], v[56:59]
	v_mfma_f32_16x16x32_bf16 v[60:63], v[152:155], v[192:195], v[60:63]
	v_mfma_f32_16x16x32_bf16 v[60:63], v[52:55], v[188:191], v[60:63]
	v_mfma_f32_16x16x32_bf16 v[44:47], v[52:55], v[196:199], v[44:47]
	v_mfma_f32_16x16x32_bf16 v[44:47], v[152:155], v[200:203], v[44:47]
	v_mfma_f32_16x16x32_bf16 v[40:43], v[160:163], v[200:203], v[40:43]
	v_mfma_f32_16x16x32_bf16 v[40:43], v[156:159], v[196:199], v[40:43]
	v_mfma_f32_16x16x32_bf16 v[20:23], v[156:159], v[204:207], v[20:23]
	v_mfma_f32_16x16x32_bf16 v[20:23], v[160:163], v[208:211], v[20:23]
	v_mfma_f32_16x16x32_bf16 v[24:27], v[152:155], v[208:211], v[24:27]
	v_mfma_f32_16x16x32_bf16 v[24:27], v[52:55], v[204:207], v[24:27]
	s_setprio 0
	s_setprio 1
	v_mfma_f32_16x16x32_bf16 v[36:39], v[164:167], v[180:183], v[36:39]
	v_mfma_f32_16x16x32_bf16 v[52:55], v[168:171], v[184:187], v[36:39]
	v_mfma_f32_16x16x32_bf16 v[36:39], v[172:175], v[180:183], v[48:51]
	v_mfma_f32_16x16x32_bf16 v[32:35], v[164:167], v[188:191], v[32:35]
	v_mfma_f32_16x16x32_bf16 v[28:31], v[172:175], v[188:191], v[28:31]
	v_mfma_f32_16x16x32_bf16 v[16:19], v[164:167], v[196:199], v[16:19]
	v_mfma_f32_16x16x32_bf16 v[12:15], v[172:175], v[196:199], v[12:15]
	v_mfma_f32_16x16x32_bf16 v[8:11], v[164:167], v[204:207], v[8:11]
	v_mfma_f32_16x16x32_bf16 v[4:7], v[172:175], v[204:207], v[4:7]
	v_mfma_f32_16x16x32_bf16 v[48:51], v[176:179], v[184:187], v[36:39]
	v_mfma_f32_16x16x32_bf16 v[32:35], v[168:171], v[192:195], v[32:35]
	v_mfma_f32_16x16x32_bf16 v[28:31], v[176:179], v[192:195], v[28:31]
	v_mfma_f32_16x16x32_bf16 v[16:19], v[168:171], v[200:203], v[16:19]
	v_mfma_f32_16x16x32_bf16 v[12:15], v[176:179], v[200:203], v[12:15]
	v_mfma_f32_16x16x32_bf16 v[8:11], v[168:171], v[208:211], v[8:11]
	v_mfma_f32_16x16x32_bf16 v[4:7], v[176:179], v[208:211], v[4:7]
	s_setprio 0
	s_barrier
	s_add_i32 s13, s13, 2
	s_add_u32 s22, s22, 0x10000
	s_addc_u32 s23, s23, 0
	s_add_u32 s82, s82, 0x10000
	s_addc_u32 vcc_lo, vcc_lo, 0
	s_cmp_gt_u32 s13, 29
	s_cbranch_scc0 .LBB0_2111
	s_and_b64 vcc, exec, s[6:7]
	s_movk_i32 s77, 0x1000
	s_cbranch_vccz .LBB0_2114
	s_barrier
